# hand-written P1 epilogue for the transposed kinds (V_g^T gelu + LayerNorm partial stats, V_a^T): both token-rstd load groups issued together, DPP row_newbcast / row_ror reductions instead of ~150 ds_b
# speedup vs baseline: 1.0057x; 1.0057x over previous
; __device__ __forceinline__ f32x4 gelu4(f32x4 v) { return (f32x4){gelu_tanh(v[0]), gelu_tanh(v[1]), gelu_tanh(v[2]), gelu_tanh(v[3])}; }
;     __device__ __forceinline__ void operator()(f32x4 (&acc)[2][2][4][2], const Unit& u, int wr, int wc, int fr, int fq) const {
;     ...
;             const bool isg = (u.kind == 1);
;             const int ch0 = (isg ? (u.pn - 4) : (u.pn - 16)) * 256 + wr * 64 + fr;
;             const int tok0 = u.pm * BM + wc * 64 + 8 * fq;
;             bf16_t* base = isg ? VTg : VTa;
; #pragma unroll
;             for (int bj = 0; bj < 2; ++bj) {
;                 const int tok = tok0 + bj * 32;
;                 f32x4 r0, r1;
;                 {
;                     const float* sp = ss + (size_t)(tok + (fr & 7)) * 32 + 16 * (fr >> 3);
;                     const f32x4 a = *(const f32x4*)sp, b = *(const f32x4*)(sp + 4), c = *(const f32x4*)(sp + 8), d = *(const f32x4*)(sp + 12);
;                     float s = (((a[0] + a[1]) + (a[2] + a[3])) + ((b[0] + b[1]) + (b[2] + b[3]))) + (((c[0] + c[1]) + (c[2] + c[3])) + ((d[0] + d[1]) + (d[2] + d[3])));
;                     s += __shfl_xor(s, 8);
;                     const float rt = __builtin_amdgcn_rsqf(s * (1.0f / D) + RMS_EPS);
;                     const int lb = (fq << 4);
; #pragma unroll
;                     for (int j = 0; j < 4; ++j) { r0[j] = __shfl(rt, lb | j); r1[j] = __shfl(rt, lb | (4 + j)); }
;                 }
;                 f32x4 s0 = {0.f, 0.f, 0.f, 0.f}, s1 = s0, q0 = s0, q1 = s0;
; #pragma unroll
;                 for (int ai = 0; ai < 2; ++ai)
; #pragma unroll
;                     for (int m = 0; m < 4; ++m) {
;                         const int ch = ch0 + ai * HALF + m * 16;
;                         f32x4 v0 = acc[ai][bj][m][0] * r0, v1 = acc[ai][bj][m][1] * r1;
;                         if (isg) { v0 = gelu4(v0); v1 = gelu4(v1); s0 += v0; s1 += v1; q0 += v0 * v0; q1 += v1 * v1; }
.LBB0_126:
	s_cmp_lg_u32 s20, 0
	s_cbranch_scc0 .LBB0_129
	v_lshl_or_b32 v184, s82, 8, v215
	v_or_b32_e32 v2, v184, v213
	v_mov_b32_e32 v3, 0
	v_lshlrev_b64 v[2:3], 7, v[2:3]
	v_lshl_add_u64 v[2:3], v[176:177], 0, v[2:3]
	v_add_co_u32_e32 v152, vcc, 0x1000, v2
	s_nop 1
	v_addc_co_u32_e32 v153, vcc, 0, v3, vcc
	global_load_dwordx4 v[186:189], v[2:3], off
	global_load_dwordx4 v[190:193], v[2:3], off offset:32
	global_load_dwordx4 v[194:197], v[2:3], off offset:16
	global_load_dwordx4 v[198:201], v[2:3], off offset:48
	global_load_dwordx4 v[132:135], v[152:153], off
	global_load_dwordx4 v[136:139], v[152:153], off offset:32
	global_load_dwordx4 v[140:143], v[152:153], off offset:16
	global_load_dwordx4 v[148:151], v[152:153], off offset:48
	s_cmp_eq_u32 s20, 1
	s_cselect_b64 s[0:1], -1, 0
	s_mov_b32 s12, 0x19c00000
	s_cselect_b32 s12, s12, 0x1ac00000
	s_cselect_b32 s16, -4, -16
	s_add_i32 s16, s16, s51
	s_add_u32 s12, s44, s12
	s_addc_u32 s13, s45, 0
	v_lshl_add_u32 v185, s16, 8, v211
	v_lshlrev_b32_e32 v185, 14, v185
	v_lshl_add_u32 v185, v184, 1, v185
	s_lshl_b32 s17, s51, 1
	s_add_i32 s17, s17, s94
	s_lshl_b32 s17, s17, 3
	v_or_b32_e32 v162, v184, v210
	v_lshlrev_b32_e32 v162, 6, v162
	v_add_u32_e32 v162, s17, v162
	s_mov_b32 s38, 0x3d372713
	s_mov_b32 s39, 0x3d372713
	s_mov_b32 s40, 0xc0135761
	s_mov_b32 s41, 0xc0135761
	s_mov_b32 s42, 1.0
	s_mov_b32 s43, 1.0
	s_waitcnt vmcnt(4)
	v_pk_add_f32 v[186:187], v[186:187], v[190:191]
	v_pk_add_f32 v[188:189], v[188:189], v[192:193]
	v_pk_add_f32 v[194:195], v[194:195], v[198:199]
	v_pk_add_f32 v[196:197], v[196:197], v[200:201]
	v_pk_add_f32 v[186:187], v[186:187], v[194:195]
	v_pk_add_f32 v[188:189], v[188:189], v[196:197]
	v_pk_add_f32 v[186:187], v[186:187], v[188:189]
	v_add_f32_e32 v250, v186, v187
	s_nop 1
	v_add_f32_dpp v250, v250, v250 row_ror:8 row_mask:0xf bank_mask:0xf
	v_fmamk_f32 v250, v250, 0x3a000000, v243
	v_rsq_f32_e32 v250, v250
	s_waitcnt vmcnt(0)
	v_pk_add_f32 v[132:133], v[132:133], v[136:137]
	v_pk_add_f32 v[134:135], v[134:135], v[138:139]
	v_pk_add_f32 v[140:141], v[140:141], v[148:149]
	v_pk_add_f32 v[142:143], v[142:143], v[150:151]
	v_pk_add_f32 v[132:133], v[132:133], v[140:141]
	v_pk_add_f32 v[134:135], v[134:135], v[142:143]
	v_pk_add_f32 v[132:133], v[132:133], v[134:135]
	v_add_f32_e32 v251, v132, v133
	s_nop 1
	v_add_f32_dpp v251, v251, v251 row_ror:8 row_mask:0xf bank_mask:0xf
	v_fmamk_f32 v251, v251, 0x3a000000, v243
	v_rsq_f32_e32 v251, v251
	s_and_b64 vcc, exec, s[0:1]
	s_cbranch_vccz .Lp1t_plain
	s_nop 1
	v_mov_b32_dpp v202, v250 row_newbcast:0 row_mask:0xf bank_mask:0xf
	v_mov_b32_dpp v203, v250 row_newbcast:1 row_mask:0xf bank_mask:0xf
	v_mov_b32_dpp v204, v250 row_newbcast:2 row_mask:0xf bank_mask:0xf
	v_mov_b32_dpp v205, v250 row_newbcast:3 row_mask:0xf bank_mask:0xf
	v_mov_b32_dpp v206, v250 row_newbcast:4 row_mask:0xf bank_mask:0xf
	v_mov_b32_dpp v207, v250 row_newbcast:5 row_mask:0xf bank_mask:0xf
	v_mov_b32_dpp v208, v250 row_newbcast:6 row_mask:0xf bank_mask:0xf
	v_mov_b32_dpp v209, v250 row_newbcast:7 row_mask:0xf bank_mask:0xf
	v_mov_b64_e32 v[186:187], 0
	v_mov_b64_e32 v[188:189], 0
	v_mov_b64_e32 v[190:191], 0
	v_mov_b64_e32 v[192:193], 0
	v_mov_b64_e32 v[194:195], 0
	v_mov_b64_e32 v[196:197], 0
	v_mov_b64_e32 v[198:199], 0
	v_mov_b64_e32 v[200:201], 0
	v_pk_mul_f32 v[128:129], v[128:129], v[202:203]
	v_pk_mul_f32 v[130:131], v[130:131], v[204:205]
	v_pk_mul_f32 v[124:125], v[124:125], v[206:207]
	v_pk_mul_f32 v[126:127], v[126:127], v[208:209]
	v_pk_mul_f32 v[218:219], v[128:129], s[38:39]
	v_pk_mul_f32 v[220:221], v[130:131], s[38:39]
	v_pk_mul_f32 v[222:223], v[124:125], s[38:39]
	v_pk_mul_f32 v[224:225], v[126:127], s[38:39]
	v_pk_mul_f32 v[218:219], v[128:129], v[218:219]
	v_pk_mul_f32 v[220:221], v[130:131], v[220:221]
	v_pk_mul_f32 v[222:223], v[124:125], v[222:223]
	v_pk_mul_f32 v[224:225], v[126:127], v[224:225]
	v_pk_fma_f32 v[218:219], v[128:129], v[218:219], v[128:129]
	v_pk_fma_f32 v[220:221], v[130:131], v[220:221], v[130:131]
	v_pk_fma_f32 v[222:223], v[124:125], v[222:223], v[124:125]
	v_pk_fma_f32 v[224:225], v[126:127], v[224:225], v[126:127]
	v_pk_mul_f32 v[218:219], v[218:219], s[40:41]
	v_pk_mul_f32 v[220:221], v[220:221], s[40:41]
	v_pk_mul_f32 v[222:223], v[222:223], s[40:41]
	v_pk_mul_f32 v[224:225], v[224:225], s[40:41]
	v_exp_f32_e32 v218, v218
	v_exp_f32_e32 v219, v219
	v_exp_f32_e32 v220, v220
	v_exp_f32_e32 v221, v221
	v_exp_f32_e32 v222, v222
	v_exp_f32_e32 v223, v223
	v_exp_f32_e32 v224, v224
	v_exp_f32_e32 v225, v225
	v_pk_add_f32 v[218:219], v[218:219], s[42:43]
	v_pk_add_f32 v[220:221], v[220:221], s[42:43]
	v_pk_add_f32 v[222:223], v[222:223], s[42:43]
	v_pk_add_f32 v[224:225], v[224:225], s[42:43]
	v_rcp_f32_e32 v218, v218
	v_rcp_f32_e32 v219, v219
	v_rcp_f32_e32 v220, v220
	v_rcp_f32_e32 v221, v221
	v_rcp_f32_e32 v222, v222
	v_rcp_f32_e32 v223, v223
	v_rcp_f32_e32 v224, v224
	v_rcp_f32_e32 v225, v225
	v_pk_mul_f32 v[218:219], v[128:129], v[218:219]
	v_pk_mul_f32 v[220:221], v[130:131], v[220:221]
	v_pk_mul_f32 v[222:223], v[124:125], v[222:223]
	v_pk_mul_f32 v[224:225], v[126:127], v[224:225]
	v_pk_add_f32 v[186:187], v[186:187], v[218:219]
	v_pk_add_f32 v[188:189], v[188:189], v[220:221]
	v_pk_add_f32 v[190:191], v[190:191], v[222:223]
	v_pk_add_f32 v[192:193], v[192:193], v[224:225]
	v_pk_fma_f32 v[194:195], v[218:219], v[218:219], v[194:195]
	v_pk_fma_f32 v[196:197], v[220:221], v[220:221], v[196:197]
	v_pk_fma_f32 v[198:199], v[222:223], v[222:223], v[198:199]
	v_pk_fma_f32 v[200:201], v[224:225], v[224:225], v[200:201]
	v_cvt_pk_bf16_f32 v226, v218, v219
	v_cvt_pk_bf16_f32 v227, v220, v221
; __device__ __forceinline__ f32x4 gelu4(f32x4 v) { return (f32x4){gelu_tanh(v[0]), gelu_tanh(v[1]), gelu_tanh(v[2]), gelu_tanh(v[3])}; }
; __device__ __forceinline__ u32x4 pack8(f32x4 a, f32x4 b) { u32x4 w; w.x = cvt_pk_bf16(a[0], a[1]); w.y = cvt_pk_bf16(a[2], a[3]); w.z = cvt_pk_bf16(b[0], b[1]); w.w = cvt_pk_bf16(b[2], b[3]); return w; }
;     __device__ __forceinline__ void operator()(f32x4 (&acc)[2][2][4][2], const Unit& u, int wr, int wc, int fr, int fq) const {
;     ...
;                 f32x4 s0 = {0.f, 0.f, 0.f, 0.f}, s1 = s0, q0 = s0, q1 = s0;
; #pragma unroll
;                 for (int ai = 0; ai < 2; ++ai)
; #pragma unroll
;                     for (int m = 0; m < 4; ++m) {
;                         const int ch = ch0 + ai * HALF + m * 16;
;                         f32x4 v0 = acc[ai][bj][m][0] * r0, v1 = acc[ai][bj][m][1] * r1;
;                         if (isg) { v0 = gelu4(v0); v1 = gelu4(v1); s0 += v0; s1 += v1; q0 += v0 * v0; q1 += v1 * v1; }
;                         *(u32x4*)(base + (size_t)ch * T + tok) = pack8(v0, v1);
	v_cvt_pk_bf16_f32 v228, v222, v223
	v_cvt_pk_bf16_f32 v229, v224, v225
	global_store_dwordx4 v185, v[226:229], s[12:13]
	v_pk_mul_f32 v[112:113], v[112:113], v[202:203]
	v_pk_mul_f32 v[114:115], v[114:115], v[204:205]
	v_pk_mul_f32 v[108:109], v[108:109], v[206:207]
	v_pk_mul_f32 v[110:111], v[110:111], v[208:209]
	v_pk_mul_f32 v[218:219], v[112:113], s[38:39]
	v_pk_mul_f32 v[220:221], v[114:115], s[38:39]
	v_pk_mul_f32 v[222:223], v[108:109], s[38:39]
	v_pk_mul_f32 v[224:225], v[110:111], s[38:39]
	v_pk_mul_f32 v[218:219], v[112:113], v[218:219]
	v_pk_mul_f32 v[220:221], v[114:115], v[220:221]
	v_pk_mul_f32 v[222:223], v[108:109], v[222:223]
	v_pk_mul_f32 v[224:225], v[110:111], v[224:225]
	v_pk_fma_f32 v[218:219], v[112:113], v[218:219], v[112:113]
	v_pk_fma_f32 v[220:221], v[114:115], v[220:221], v[114:115]
	v_pk_fma_f32 v[222:223], v[108:109], v[222:223], v[108:109]
	v_pk_fma_f32 v[224:225], v[110:111], v[224:225], v[110:111]
	v_pk_mul_f32 v[218:219], v[218:219], s[40:41]
	v_pk_mul_f32 v[220:221], v[220:221], s[40:41]
	v_pk_mul_f32 v[222:223], v[222:223], s[40:41]
	v_pk_mul_f32 v[224:225], v[224:225], s[40:41]
	v_exp_f32_e32 v218, v218
	v_exp_f32_e32 v219, v219
	v_exp_f32_e32 v220, v220
	v_exp_f32_e32 v221, v221
	v_exp_f32_e32 v222, v222
	v_exp_f32_e32 v223, v223
	v_exp_f32_e32 v224, v224
	v_exp_f32_e32 v225, v225
	v_pk_add_f32 v[218:219], v[218:219], s[42:43]
	v_pk_add_f32 v[220:221], v[220:221], s[42:43]
	v_pk_add_f32 v[222:223], v[222:223], s[42:43]
	v_pk_add_f32 v[224:225], v[224:225], s[42:43]
	v_rcp_f32_e32 v218, v218
	v_rcp_f32_e32 v219, v219
	v_rcp_f32_e32 v220, v220
	v_rcp_f32_e32 v221, v221
	v_rcp_f32_e32 v222, v222
	v_rcp_f32_e32 v223, v223
	v_rcp_f32_e32 v224, v224
	v_rcp_f32_e32 v225, v225
	v_pk_mul_f32 v[218:219], v[112:113], v[218:219]
	v_pk_mul_f32 v[220:221], v[114:115], v[220:221]
	v_pk_mul_f32 v[222:223], v[108:109], v[222:223]
	v_pk_mul_f32 v[224:225], v[110:111], v[224:225]
	v_pk_add_f32 v[186:187], v[186:187], v[218:219]
	v_pk_add_f32 v[188:189], v[188:189], v[220:221]
	v_pk_add_f32 v[190:191], v[190:191], v[222:223]
	v_pk_add_f32 v[192:193], v[192:193], v[224:225]
	v_pk_fma_f32 v[194:195], v[218:219], v[218:219], v[194:195]
	v_pk_fma_f32 v[196:197], v[220:221], v[220:221], v[196:197]
	v_pk_fma_f32 v[198:199], v[222:223], v[222:223], v[198:199]
	v_pk_fma_f32 v[200:201], v[224:225], v[224:225], v[200:201]
	v_cvt_pk_bf16_f32 v132, v218, v219
	v_cvt_pk_bf16_f32 v133, v220, v221
	v_cvt_pk_bf16_f32 v134, v222, v223
	v_cvt_pk_bf16_f32 v135, v224, v225
	v_add_u32_e32 v0, 0x40000, v185
	global_store_dwordx4 v0, v[132:135], s[12:13]
	v_pk_mul_f32 v[96:97], v[96:97], v[202:203]
	v_pk_mul_f32 v[98:99], v[98:99], v[204:205]
	v_pk_mul_f32 v[92:93], v[92:93], v[206:207]
	v_pk_mul_f32 v[94:95], v[94:95], v[208:209]
	v_pk_mul_f32 v[218:219], v[96:97], s[38:39]
	v_pk_mul_f32 v[220:221], v[98:99], s[38:39]
	v_pk_mul_f32 v[222:223], v[92:93], s[38:39]
	v_pk_mul_f32 v[224:225], v[94:95], s[38:39]
	v_pk_mul_f32 v[218:219], v[96:97], v[218:219]
	v_pk_mul_f32 v[220:221], v[98:99], v[220:221]
	v_pk_mul_f32 v[222:223], v[92:93], v[222:223]
	v_pk_mul_f32 v[224:225], v[94:95], v[224:225]
	v_pk_fma_f32 v[218:219], v[96:97], v[218:219], v[96:97]
	v_pk_fma_f32 v[220:221], v[98:99], v[220:221], v[98:99]
	v_pk_fma_f32 v[222:223], v[92:93], v[222:223], v[92:93]
	v_pk_fma_f32 v[224:225], v[94:95], v[224:225], v[94:95]
	v_pk_mul_f32 v[218:219], v[218:219], s[40:41]
	v_pk_mul_f32 v[220:221], v[220:221], s[40:41]
	v_pk_mul_f32 v[222:223], v[222:223], s[40:41]
	v_pk_mul_f32 v[224:225], v[224:225], s[40:41]
	v_exp_f32_e32 v218, v218
	v_exp_f32_e32 v219, v219
	v_exp_f32_e32 v220, v220
	v_exp_f32_e32 v221, v221
	v_exp_f32_e32 v222, v222
	v_exp_f32_e32 v223, v223
	v_exp_f32_e32 v224, v224
	v_exp_f32_e32 v225, v225
	v_pk_add_f32 v[218:219], v[218:219], s[42:43]
	v_pk_add_f32 v[220:221], v[220:221], s[42:43]
	v_pk_add_f32 v[222:223], v[222:223], s[42:43]
	v_pk_add_f32 v[224:225], v[224:225], s[42:43]
	v_rcp_f32_e32 v218, v218
	v_rcp_f32_e32 v219, v219
	v_rcp_f32_e32 v220, v220
	v_rcp_f32_e32 v221, v221
	v_rcp_f32_e32 v222, v222
	v_rcp_f32_e32 v223, v223
	v_rcp_f32_e32 v224, v224
	v_rcp_f32_e32 v225, v225
	v_pk_mul_f32 v[218:219], v[96:97], v[218:219]
	v_pk_mul_f32 v[220:221], v[98:99], v[220:221]
	v_pk_mul_f32 v[222:223], v[92:93], v[222:223]
	v_pk_mul_f32 v[224:225], v[94:95], v[224:225]
	v_pk_add_f32 v[186:187], v[186:187], v[218:219]
	v_pk_add_f32 v[188:189], v[188:189], v[220:221]
	v_pk_add_f32 v[190:191], v[190:191], v[222:223]
	v_pk_add_f32 v[192:193], v[192:193], v[224:225]
	v_pk_fma_f32 v[194:195], v[218:219], v[218:219], v[194:195]
	v_pk_fma_f32 v[196:197], v[220:221], v[220:221], v[196:197]
	v_pk_fma_f32 v[198:199], v[222:223], v[222:223], v[198:199]
	v_pk_fma_f32 v[200:201], v[224:225], v[224:225], v[200:201]
	v_cvt_pk_bf16_f32 v226, v218, v219
	v_cvt_pk_bf16_f32 v227, v220, v221
	v_cvt_pk_bf16_f32 v228, v222, v223
	v_cvt_pk_bf16_f32 v229, v224, v225
	v_add_u32_e32 v0, 0x80000, v185
	global_store_dwordx4 v0, v[226:229], s[12:13]
	v_pk_mul_f32 v[80:81], v[80:81], v[202:203]
	v_pk_mul_f32 v[82:83], v[82:83], v[204:205]
	v_pk_mul_f32 v[76:77], v[76:77], v[206:207]
	v_pk_mul_f32 v[78:79], v[78:79], v[208:209]
	v_pk_mul_f32 v[218:219], v[80:81], s[38:39]
	v_pk_mul_f32 v[220:221], v[82:83], s[38:39]
	v_pk_mul_f32 v[222:223], v[76:77], s[38:39]
	v_pk_mul_f32 v[224:225], v[78:79], s[38:39]
	v_pk_mul_f32 v[218:219], v[80:81], v[218:219]
	v_pk_mul_f32 v[220:221], v[82:83], v[220:221]
	v_pk_mul_f32 v[222:223], v[76:77], v[222:223]
	v_pk_mul_f32 v[224:225], v[78:79], v[224:225]
	v_pk_fma_f32 v[218:219], v[80:81], v[218:219], v[80:81]
; __device__ __forceinline__ f32x4 gelu4(f32x4 v) { return (f32x4){gelu_tanh(v[0]), gelu_tanh(v[1]), gelu_tanh(v[2]), gelu_tanh(v[3])}; }
; __device__ __forceinline__ u32x4 pack8(f32x4 a, f32x4 b) { u32x4 w; w.x = cvt_pk_bf16(a[0], a[1]); w.y = cvt_pk_bf16(a[2], a[3]); w.z = cvt_pk_bf16(b[0], b[1]); w.w = cvt_pk_bf16(b[2], b[3]); return w; }
;     __device__ __forceinline__ void operator()(f32x4 (&acc)[2][2][4][2], const Unit& u, int wr, int wc, int fr, int fq) const {
;     ...
;                 f32x4 s0 = {0.f, 0.f, 0.f, 0.f}, s1 = s0, q0 = s0, q1 = s0;
; #pragma unroll
;                 for (int ai = 0; ai < 2; ++ai)
; #pragma unroll
;                     for (int m = 0; m < 4; ++m) {
;                         const int ch = ch0 + ai * HALF + m * 16;
;                         f32x4 v0 = acc[ai][bj][m][0] * r0, v1 = acc[ai][bj][m][1] * r1;
;                         if (isg) { v0 = gelu4(v0); v1 = gelu4(v1); s0 += v0; s1 += v1; q0 += v0 * v0; q1 += v1 * v1; }
;                         *(u32x4*)(base + (size_t)ch * T + tok) = pack8(v0, v1);
	v_pk_fma_f32 v[220:221], v[82:83], v[220:221], v[82:83]
	v_pk_fma_f32 v[222:223], v[76:77], v[222:223], v[76:77]
	v_pk_fma_f32 v[224:225], v[78:79], v[224:225], v[78:79]
	v_pk_mul_f32 v[218:219], v[218:219], s[40:41]
	v_pk_mul_f32 v[220:221], v[220:221], s[40:41]
	v_pk_mul_f32 v[222:223], v[222:223], s[40:41]
	v_pk_mul_f32 v[224:225], v[224:225], s[40:41]
	v_exp_f32_e32 v218, v218
	v_exp_f32_e32 v219, v219
	v_exp_f32_e32 v220, v220
	v_exp_f32_e32 v221, v221
	v_exp_f32_e32 v222, v222
	v_exp_f32_e32 v223, v223
	v_exp_f32_e32 v224, v224
	v_exp_f32_e32 v225, v225
	v_pk_add_f32 v[218:219], v[218:219], s[42:43]
	v_pk_add_f32 v[220:221], v[220:221], s[42:43]
	v_pk_add_f32 v[222:223], v[222:223], s[42:43]
	v_pk_add_f32 v[224:225], v[224:225], s[42:43]
	v_rcp_f32_e32 v218, v218
	v_rcp_f32_e32 v219, v219
	v_rcp_f32_e32 v220, v220
	v_rcp_f32_e32 v221, v221
	v_rcp_f32_e32 v222, v222
	v_rcp_f32_e32 v223, v223
	v_rcp_f32_e32 v224, v224
	v_rcp_f32_e32 v225, v225
	v_pk_mul_f32 v[218:219], v[80:81], v[218:219]
	v_pk_mul_f32 v[220:221], v[82:83], v[220:221]
	v_pk_mul_f32 v[222:223], v[76:77], v[222:223]
	v_pk_mul_f32 v[224:225], v[78:79], v[224:225]
	v_pk_add_f32 v[186:187], v[186:187], v[218:219]
	v_pk_add_f32 v[188:189], v[188:189], v[220:221]
	v_pk_add_f32 v[190:191], v[190:191], v[222:223]
	v_pk_add_f32 v[192:193], v[192:193], v[224:225]
	v_pk_fma_f32 v[194:195], v[218:219], v[218:219], v[194:195]
	v_pk_fma_f32 v[196:197], v[220:221], v[220:221], v[196:197]
	v_pk_fma_f32 v[198:199], v[222:223], v[222:223], v[198:199]
	v_pk_fma_f32 v[200:201], v[224:225], v[224:225], v[200:201]
	v_cvt_pk_bf16_f32 v132, v218, v219
	v_cvt_pk_bf16_f32 v133, v220, v221
	v_cvt_pk_bf16_f32 v134, v222, v223
	v_cvt_pk_bf16_f32 v135, v224, v225
	v_add_u32_e32 v0, 0xc0000, v185
	global_store_dwordx4 v0, v[132:135], s[12:13]
	v_pk_mul_f32 v[64:65], v[64:65], v[202:203]
	v_pk_mul_f32 v[66:67], v[66:67], v[204:205]
	v_pk_mul_f32 v[60:61], v[60:61], v[206:207]
	v_pk_mul_f32 v[62:63], v[62:63], v[208:209]
	v_pk_mul_f32 v[218:219], v[64:65], s[38:39]
	v_pk_mul_f32 v[220:221], v[66:67], s[38:39]
	v_pk_mul_f32 v[222:223], v[60:61], s[38:39]
	v_pk_mul_f32 v[224:225], v[62:63], s[38:39]
	v_pk_mul_f32 v[218:219], v[64:65], v[218:219]
	v_pk_mul_f32 v[220:221], v[66:67], v[220:221]
	v_pk_mul_f32 v[222:223], v[60:61], v[222:223]
	v_pk_mul_f32 v[224:225], v[62:63], v[224:225]
	v_pk_fma_f32 v[218:219], v[64:65], v[218:219], v[64:65]
	v_pk_fma_f32 v[220:221], v[66:67], v[220:221], v[66:67]
	v_pk_fma_f32 v[222:223], v[60:61], v[222:223], v[60:61]
	v_pk_fma_f32 v[224:225], v[62:63], v[224:225], v[62:63]
	v_pk_mul_f32 v[218:219], v[218:219], s[40:41]
	v_pk_mul_f32 v[220:221], v[220:221], s[40:41]
	v_pk_mul_f32 v[222:223], v[222:223], s[40:41]
	v_pk_mul_f32 v[224:225], v[224:225], s[40:41]
	v_exp_f32_e32 v218, v218
	v_exp_f32_e32 v219, v219
	v_exp_f32_e32 v220, v220
	v_exp_f32_e32 v221, v221
	v_exp_f32_e32 v222, v222
	v_exp_f32_e32 v223, v223
	v_exp_f32_e32 v224, v224
	v_exp_f32_e32 v225, v225
	v_pk_add_f32 v[218:219], v[218:219], s[42:43]
	v_pk_add_f32 v[220:221], v[220:221], s[42:43]
	v_pk_add_f32 v[222:223], v[222:223], s[42:43]
	v_pk_add_f32 v[224:225], v[224:225], s[42:43]
	v_rcp_f32_e32 v218, v218
	v_rcp_f32_e32 v219, v219
	v_rcp_f32_e32 v220, v220
	v_rcp_f32_e32 v221, v221
	v_rcp_f32_e32 v222, v222
	v_rcp_f32_e32 v223, v223
	v_rcp_f32_e32 v224, v224
	v_rcp_f32_e32 v225, v225
	v_pk_mul_f32 v[218:219], v[64:65], v[218:219]
	v_pk_mul_f32 v[220:221], v[66:67], v[220:221]
	v_pk_mul_f32 v[222:223], v[60:61], v[222:223]
	v_pk_mul_f32 v[224:225], v[62:63], v[224:225]
	v_pk_add_f32 v[186:187], v[186:187], v[218:219]
	v_pk_add_f32 v[188:189], v[188:189], v[220:221]
	v_pk_add_f32 v[190:191], v[190:191], v[222:223]
	v_pk_add_f32 v[192:193], v[192:193], v[224:225]
	v_pk_fma_f32 v[194:195], v[218:219], v[218:219], v[194:195]
	v_pk_fma_f32 v[196:197], v[220:221], v[220:221], v[196:197]
	v_pk_fma_f32 v[198:199], v[222:223], v[222:223], v[198:199]
	v_pk_fma_f32 v[200:201], v[224:225], v[224:225], v[200:201]
	v_cvt_pk_bf16_f32 v226, v218, v219
	v_cvt_pk_bf16_f32 v227, v220, v221
	v_cvt_pk_bf16_f32 v228, v222, v223
	v_cvt_pk_bf16_f32 v229, v224, v225
	v_add_u32_e32 v0, 0x200000, v185
	global_store_dwordx4 v0, v[226:229], s[12:13]
	v_pk_mul_f32 v[48:49], v[48:49], v[202:203]
	v_pk_mul_f32 v[50:51], v[50:51], v[204:205]
	v_pk_mul_f32 v[44:45], v[44:45], v[206:207]
	v_pk_mul_f32 v[46:47], v[46:47], v[208:209]
	v_pk_mul_f32 v[218:219], v[48:49], s[38:39]
	v_pk_mul_f32 v[220:221], v[50:51], s[38:39]
	v_pk_mul_f32 v[222:223], v[44:45], s[38:39]
	v_pk_mul_f32 v[224:225], v[46:47], s[38:39]
	v_pk_mul_f32 v[218:219], v[48:49], v[218:219]
	v_pk_mul_f32 v[220:221], v[50:51], v[220:221]
	v_pk_mul_f32 v[222:223], v[44:45], v[222:223]
	v_pk_mul_f32 v[224:225], v[46:47], v[224:225]
	v_pk_fma_f32 v[218:219], v[48:49], v[218:219], v[48:49]
	v_pk_fma_f32 v[220:221], v[50:51], v[220:221], v[50:51]
	v_pk_fma_f32 v[222:223], v[44:45], v[222:223], v[44:45]
	v_pk_fma_f32 v[224:225], v[46:47], v[224:225], v[46:47]
	v_pk_mul_f32 v[218:219], v[218:219], s[40:41]
	v_pk_mul_f32 v[220:221], v[220:221], s[40:41]
	v_pk_mul_f32 v[222:223], v[222:223], s[40:41]
	v_pk_mul_f32 v[224:225], v[224:225], s[40:41]
	v_exp_f32_e32 v218, v218
	v_exp_f32_e32 v219, v219
	v_exp_f32_e32 v220, v220
	v_exp_f32_e32 v221, v221
	v_exp_f32_e32 v222, v222
	v_exp_f32_e32 v223, v223
	v_exp_f32_e32 v224, v224
	v_exp_f32_e32 v225, v225
	v_pk_add_f32 v[218:219], v[218:219], s[42:43]
	v_pk_add_f32 v[220:221], v[220:221], s[42:43]
	v_pk_add_f32 v[222:223], v[222:223], s[42:43]
	v_pk_add_f32 v[224:225], v[224:225], s[42:43]
	v_rcp_f32_e32 v218, v218
	v_rcp_f32_e32 v219, v219
; __device__ __forceinline__ f32x4 gelu4(f32x4 v) { return (f32x4){gelu_tanh(v[0]), gelu_tanh(v[1]), gelu_tanh(v[2]), gelu_tanh(v[3])}; }
; __device__ __forceinline__ u32x4 pack8(f32x4 a, f32x4 b) { u32x4 w; w.x = cvt_pk_bf16(a[0], a[1]); w.y = cvt_pk_bf16(a[2], a[3]); w.z = cvt_pk_bf16(b[0], b[1]); w.w = cvt_pk_bf16(b[2], b[3]); return w; }
;     __device__ __forceinline__ void operator()(f32x4 (&acc)[2][2][4][2], const Unit& u, int wr, int wc, int fr, int fq) const {
;     ...
;                 f32x4 s0 = {0.f, 0.f, 0.f, 0.f}, s1 = s0, q0 = s0, q1 = s0;
; #pragma unroll
;                 for (int ai = 0; ai < 2; ++ai)
; #pragma unroll
;                     for (int m = 0; m < 4; ++m) {
;                         const int ch = ch0 + ai * HALF + m * 16;
;                         f32x4 v0 = acc[ai][bj][m][0] * r0, v1 = acc[ai][bj][m][1] * r1;
;                         if (isg) { v0 = gelu4(v0); v1 = gelu4(v1); s0 += v0; s1 += v1; q0 += v0 * v0; q1 += v1 * v1; }
;                         *(u32x4*)(base + (size_t)ch * T + tok) = pack8(v0, v1);
	v_rcp_f32_e32 v220, v220
	v_rcp_f32_e32 v221, v221
	v_rcp_f32_e32 v222, v222
	v_rcp_f32_e32 v223, v223
	v_rcp_f32_e32 v224, v224
	v_rcp_f32_e32 v225, v225
	v_pk_mul_f32 v[218:219], v[48:49], v[218:219]
	v_pk_mul_f32 v[220:221], v[50:51], v[220:221]
	v_pk_mul_f32 v[222:223], v[44:45], v[222:223]
	v_pk_mul_f32 v[224:225], v[46:47], v[224:225]
	v_pk_add_f32 v[186:187], v[186:187], v[218:219]
	v_pk_add_f32 v[188:189], v[188:189], v[220:221]
	v_pk_add_f32 v[190:191], v[190:191], v[222:223]
	v_pk_add_f32 v[192:193], v[192:193], v[224:225]
	v_pk_fma_f32 v[194:195], v[218:219], v[218:219], v[194:195]
	v_pk_fma_f32 v[196:197], v[220:221], v[220:221], v[196:197]
	v_pk_fma_f32 v[198:199], v[222:223], v[222:223], v[198:199]
	v_pk_fma_f32 v[200:201], v[224:225], v[224:225], v[200:201]
	v_cvt_pk_bf16_f32 v132, v218, v219
	v_cvt_pk_bf16_f32 v133, v220, v221
	v_cvt_pk_bf16_f32 v134, v222, v223
	v_cvt_pk_bf16_f32 v135, v224, v225
	v_add_u32_e32 v0, 0x240000, v185
	global_store_dwordx4 v0, v[132:135], s[12:13]
	v_pk_mul_f32 v[32:33], v[32:33], v[202:203]
	v_pk_mul_f32 v[34:35], v[34:35], v[204:205]
	v_pk_mul_f32 v[28:29], v[28:29], v[206:207]
	v_pk_mul_f32 v[30:31], v[30:31], v[208:209]
	v_pk_mul_f32 v[218:219], v[32:33], s[38:39]
	v_pk_mul_f32 v[220:221], v[34:35], s[38:39]
	v_pk_mul_f32 v[222:223], v[28:29], s[38:39]
	v_pk_mul_f32 v[224:225], v[30:31], s[38:39]
	v_pk_mul_f32 v[218:219], v[32:33], v[218:219]
	v_pk_mul_f32 v[220:221], v[34:35], v[220:221]
	v_pk_mul_f32 v[222:223], v[28:29], v[222:223]
	v_pk_mul_f32 v[224:225], v[30:31], v[224:225]
	v_pk_fma_f32 v[218:219], v[32:33], v[218:219], v[32:33]
	v_pk_fma_f32 v[220:221], v[34:35], v[220:221], v[34:35]
	v_pk_fma_f32 v[222:223], v[28:29], v[222:223], v[28:29]
	v_pk_fma_f32 v[224:225], v[30:31], v[224:225], v[30:31]
	v_pk_mul_f32 v[218:219], v[218:219], s[40:41]
	v_pk_mul_f32 v[220:221], v[220:221], s[40:41]
	v_pk_mul_f32 v[222:223], v[222:223], s[40:41]
	v_pk_mul_f32 v[224:225], v[224:225], s[40:41]
	v_exp_f32_e32 v218, v218
	v_exp_f32_e32 v219, v219
	v_exp_f32_e32 v220, v220
	v_exp_f32_e32 v221, v221
	v_exp_f32_e32 v222, v222
	v_exp_f32_e32 v223, v223
	v_exp_f32_e32 v224, v224
	v_exp_f32_e32 v225, v225
	v_pk_add_f32 v[218:219], v[218:219], s[42:43]
	v_pk_add_f32 v[220:221], v[220:221], s[42:43]
	v_pk_add_f32 v[222:223], v[222:223], s[42:43]
	v_pk_add_f32 v[224:225], v[224:225], s[42:43]
	v_rcp_f32_e32 v218, v218
	v_rcp_f32_e32 v219, v219
	v_rcp_f32_e32 v220, v220
	v_rcp_f32_e32 v221, v221
	v_rcp_f32_e32 v222, v222
	v_rcp_f32_e32 v223, v223
	v_rcp_f32_e32 v224, v224
	v_rcp_f32_e32 v225, v225
	v_pk_mul_f32 v[218:219], v[32:33], v[218:219]
	v_pk_mul_f32 v[220:221], v[34:35], v[220:221]
	v_pk_mul_f32 v[222:223], v[28:29], v[222:223]
	v_pk_mul_f32 v[224:225], v[30:31], v[224:225]
	v_pk_add_f32 v[186:187], v[186:187], v[218:219]
	v_pk_add_f32 v[188:189], v[188:189], v[220:221]
	v_pk_add_f32 v[190:191], v[190:191], v[222:223]
	v_pk_add_f32 v[192:193], v[192:193], v[224:225]
	v_pk_fma_f32 v[194:195], v[218:219], v[218:219], v[194:195]
	v_pk_fma_f32 v[196:197], v[220:221], v[220:221], v[196:197]
	v_pk_fma_f32 v[198:199], v[222:223], v[222:223], v[198:199]
	v_pk_fma_f32 v[200:201], v[224:225], v[224:225], v[200:201]
	v_cvt_pk_bf16_f32 v226, v218, v219
	v_cvt_pk_bf16_f32 v227, v220, v221
	v_cvt_pk_bf16_f32 v228, v222, v223
	v_cvt_pk_bf16_f32 v229, v224, v225
	v_add_u32_e32 v0, 0x280000, v185
	global_store_dwordx4 v0, v[226:229], s[12:13]
	v_pk_mul_f32 v[16:17], v[16:17], v[202:203]
	v_pk_mul_f32 v[18:19], v[18:19], v[204:205]
	v_pk_mul_f32 v[12:13], v[12:13], v[206:207]
	v_pk_mul_f32 v[14:15], v[14:15], v[208:209]
	v_pk_mul_f32 v[218:219], v[16:17], s[38:39]
	v_pk_mul_f32 v[220:221], v[18:19], s[38:39]
	v_pk_mul_f32 v[222:223], v[12:13], s[38:39]
	v_pk_mul_f32 v[224:225], v[14:15], s[38:39]
	v_pk_mul_f32 v[218:219], v[16:17], v[218:219]
	v_pk_mul_f32 v[220:221], v[18:19], v[220:221]
	v_pk_mul_f32 v[222:223], v[12:13], v[222:223]
	v_pk_mul_f32 v[224:225], v[14:15], v[224:225]
	v_pk_fma_f32 v[218:219], v[16:17], v[218:219], v[16:17]
	v_pk_fma_f32 v[220:221], v[18:19], v[220:221], v[18:19]
	v_pk_fma_f32 v[222:223], v[12:13], v[222:223], v[12:13]
	v_pk_fma_f32 v[224:225], v[14:15], v[224:225], v[14:15]
	v_pk_mul_f32 v[218:219], v[218:219], s[40:41]
	v_pk_mul_f32 v[220:221], v[220:221], s[40:41]
	v_pk_mul_f32 v[222:223], v[222:223], s[40:41]
	v_pk_mul_f32 v[224:225], v[224:225], s[40:41]
	v_exp_f32_e32 v218, v218
	v_exp_f32_e32 v219, v219
	v_exp_f32_e32 v220, v220
	v_exp_f32_e32 v221, v221
	v_exp_f32_e32 v222, v222
	v_exp_f32_e32 v223, v223
	v_exp_f32_e32 v224, v224
	v_exp_f32_e32 v225, v225
	v_pk_add_f32 v[218:219], v[218:219], s[42:43]
	v_pk_add_f32 v[220:221], v[220:221], s[42:43]
	v_pk_add_f32 v[222:223], v[222:223], s[42:43]
	v_pk_add_f32 v[224:225], v[224:225], s[42:43]
	v_rcp_f32_e32 v218, v218
	v_rcp_f32_e32 v219, v219
	v_rcp_f32_e32 v220, v220
	v_rcp_f32_e32 v221, v221
	v_rcp_f32_e32 v222, v222
	v_rcp_f32_e32 v223, v223
	v_rcp_f32_e32 v224, v224
	v_rcp_f32_e32 v225, v225
	v_pk_mul_f32 v[218:219], v[16:17], v[218:219]
	v_pk_mul_f32 v[220:221], v[18:19], v[220:221]
	v_pk_mul_f32 v[222:223], v[12:13], v[222:223]
	v_pk_mul_f32 v[224:225], v[14:15], v[224:225]
	v_pk_add_f32 v[186:187], v[186:187], v[218:219]
	v_pk_add_f32 v[188:189], v[188:189], v[220:221]
	v_pk_add_f32 v[190:191], v[190:191], v[222:223]
	v_pk_add_f32 v[192:193], v[192:193], v[224:225]
	v_pk_fma_f32 v[194:195], v[218:219], v[218:219], v[194:195]
	v_pk_fma_f32 v[196:197], v[220:221], v[220:221], v[196:197]
	v_pk_fma_f32 v[198:199], v[222:223], v[222:223], v[198:199]
	v_pk_fma_f32 v[200:201], v[224:225], v[224:225], v[200:201]
; __device__ __forceinline__ u32x4 pack8(f32x4 a, f32x4 b) { u32x4 w; w.x = cvt_pk_bf16(a[0], a[1]); w.y = cvt_pk_bf16(a[2], a[3]); w.z = cvt_pk_bf16(b[0], b[1]); w.w = cvt_pk_bf16(b[2], b[3]); return w; }
;     __device__ __forceinline__ void operator()(f32x4 (&acc)[2][2][4][2], const Unit& u, int wr, int wc, int fr, int fq) const {
;     ...
;                         *(u32x4*)(base + (size_t)ch * T + tok) = pack8(v0, v1);
;                     }
;                 if (isg) {
; #pragma unroll
;                     for (int o = 1; o < 16; o <<= 1) {
; #pragma unroll
;                         for (int j = 0; j < 4; ++j) { s0[j] += __shfl_xor(s0[j], o); s1[j] += __shfl_xor(s1[j], o); q0[j] += __shfl_xor(q0[j], o); q1[j] += __shfl_xor(q1[j], o); }
;                     }
; #pragma unroll
;                     for (int j = 0; j < 4; ++j) {
;                         const int pidx = (u.pn - 4) * 2 + wr;
;                         if (fr == j)     *(f32x2*)(lns + ((size_t)(tok + j) * 8 + pidx) * 2) = (f32x2){s0[j], q0[j]};
;                         if (fr == 4 + j) *(f32x2*)(lns + ((size_t)(tok + 4 + j) * 8 + pidx) * 2) = (f32x2){s1[j], q1[j]};
;                     }
	v_cvt_pk_bf16_f32 v132, v218, v219
	v_cvt_pk_bf16_f32 v133, v220, v221
	v_cvt_pk_bf16_f32 v134, v222, v223
	v_cvt_pk_bf16_f32 v135, v224, v225
	v_add_u32_e32 v0, 0x2c0000, v185
	global_store_dwordx4 v0, v[132:135], s[12:13]
	v_add_f32_dpp v186, v186, v186 row_ror:8 row_mask:0xf bank_mask:0xf
	v_add_f32_dpp v187, v187, v187 row_ror:8 row_mask:0xf bank_mask:0xf
	v_add_f32_dpp v188, v188, v188 row_ror:8 row_mask:0xf bank_mask:0xf
	v_add_f32_dpp v189, v189, v189 row_ror:8 row_mask:0xf bank_mask:0xf
	v_add_f32_dpp v190, v190, v190 row_ror:8 row_mask:0xf bank_mask:0xf
	v_add_f32_dpp v191, v191, v191 row_ror:8 row_mask:0xf bank_mask:0xf
	v_add_f32_dpp v192, v192, v192 row_ror:8 row_mask:0xf bank_mask:0xf
	v_add_f32_dpp v193, v193, v193 row_ror:8 row_mask:0xf bank_mask:0xf
	v_add_f32_dpp v194, v194, v194 row_ror:8 row_mask:0xf bank_mask:0xf
	v_add_f32_dpp v195, v195, v195 row_ror:8 row_mask:0xf bank_mask:0xf
	v_add_f32_dpp v196, v196, v196 row_ror:8 row_mask:0xf bank_mask:0xf
	v_add_f32_dpp v197, v197, v197 row_ror:8 row_mask:0xf bank_mask:0xf
	v_add_f32_dpp v198, v198, v198 row_ror:8 row_mask:0xf bank_mask:0xf
	v_add_f32_dpp v199, v199, v199 row_ror:8 row_mask:0xf bank_mask:0xf
	v_add_f32_dpp v200, v200, v200 row_ror:8 row_mask:0xf bank_mask:0xf
	v_add_f32_dpp v201, v201, v201 row_ror:8 row_mask:0xf bank_mask:0xf
	v_add_f32_dpp v186, v186, v186 row_ror:4 row_mask:0xf bank_mask:0xf
	v_add_f32_dpp v187, v187, v187 row_ror:4 row_mask:0xf bank_mask:0xf
	v_add_f32_dpp v188, v188, v188 row_ror:4 row_mask:0xf bank_mask:0xf
	v_add_f32_dpp v189, v189, v189 row_ror:4 row_mask:0xf bank_mask:0xf
	v_add_f32_dpp v190, v190, v190 row_ror:4 row_mask:0xf bank_mask:0xf
	v_add_f32_dpp v191, v191, v191 row_ror:4 row_mask:0xf bank_mask:0xf
	v_add_f32_dpp v192, v192, v192 row_ror:4 row_mask:0xf bank_mask:0xf
	v_add_f32_dpp v193, v193, v193 row_ror:4 row_mask:0xf bank_mask:0xf
	v_add_f32_dpp v194, v194, v194 row_ror:4 row_mask:0xf bank_mask:0xf
	v_add_f32_dpp v195, v195, v195 row_ror:4 row_mask:0xf bank_mask:0xf
	v_add_f32_dpp v196, v196, v196 row_ror:4 row_mask:0xf bank_mask:0xf
	v_add_f32_dpp v197, v197, v197 row_ror:4 row_mask:0xf bank_mask:0xf
	v_add_f32_dpp v198, v198, v198 row_ror:4 row_mask:0xf bank_mask:0xf
	v_add_f32_dpp v199, v199, v199 row_ror:4 row_mask:0xf bank_mask:0xf
	v_add_f32_dpp v200, v200, v200 row_ror:4 row_mask:0xf bank_mask:0xf
	v_add_f32_dpp v201, v201, v201 row_ror:4 row_mask:0xf bank_mask:0xf
	v_add_f32_dpp v186, v186, v186 row_ror:2 row_mask:0xf bank_mask:0xf
	v_add_f32_dpp v187, v187, v187 row_ror:2 row_mask:0xf bank_mask:0xf
	v_add_f32_dpp v188, v188, v188 row_ror:2 row_mask:0xf bank_mask:0xf
	v_add_f32_dpp v189, v189, v189 row_ror:2 row_mask:0xf bank_mask:0xf
	v_add_f32_dpp v190, v190, v190 row_ror:2 row_mask:0xf bank_mask:0xf
	v_add_f32_dpp v191, v191, v191 row_ror:2 row_mask:0xf bank_mask:0xf
	v_add_f32_dpp v192, v192, v192 row_ror:2 row_mask:0xf bank_mask:0xf
	v_add_f32_dpp v193, v193, v193 row_ror:2 row_mask:0xf bank_mask:0xf
	v_add_f32_dpp v194, v194, v194 row_ror:2 row_mask:0xf bank_mask:0xf
	v_add_f32_dpp v195, v195, v195 row_ror:2 row_mask:0xf bank_mask:0xf
	v_add_f32_dpp v196, v196, v196 row_ror:2 row_mask:0xf bank_mask:0xf
	v_add_f32_dpp v197, v197, v197 row_ror:2 row_mask:0xf bank_mask:0xf
	v_add_f32_dpp v198, v198, v198 row_ror:2 row_mask:0xf bank_mask:0xf
	v_add_f32_dpp v199, v199, v199 row_ror:2 row_mask:0xf bank_mask:0xf
	v_add_f32_dpp v200, v200, v200 row_ror:2 row_mask:0xf bank_mask:0xf
	v_add_f32_dpp v201, v201, v201 row_ror:2 row_mask:0xf bank_mask:0xf
	v_add_f32_dpp v186, v186, v186 row_ror:1 row_mask:0xf bank_mask:0xf
	v_add_f32_dpp v187, v187, v187 row_ror:1 row_mask:0xf bank_mask:0xf
	v_add_f32_dpp v188, v188, v188 row_ror:1 row_mask:0xf bank_mask:0xf
	v_add_f32_dpp v189, v189, v189 row_ror:1 row_mask:0xf bank_mask:0xf
	v_add_f32_dpp v190, v190, v190 row_ror:1 row_mask:0xf bank_mask:0xf
	v_add_f32_dpp v191, v191, v191 row_ror:1 row_mask:0xf bank_mask:0xf
	v_add_f32_dpp v192, v192, v192 row_ror:1 row_mask:0xf bank_mask:0xf
	v_add_f32_dpp v193, v193, v193 row_ror:1 row_mask:0xf bank_mask:0xf
	v_add_f32_dpp v194, v194, v194 row_ror:1 row_mask:0xf bank_mask:0xf
	v_add_f32_dpp v195, v195, v195 row_ror:1 row_mask:0xf bank_mask:0xf
	v_add_f32_dpp v196, v196, v196 row_ror:1 row_mask:0xf bank_mask:0xf
	v_add_f32_dpp v197, v197, v197 row_ror:1 row_mask:0xf bank_mask:0xf
	v_add_f32_dpp v198, v198, v198 row_ror:1 row_mask:0xf bank_mask:0xf
	v_add_f32_dpp v199, v199, v199 row_ror:1 row_mask:0xf bank_mask:0xf
	v_add_f32_dpp v200, v200, v200 row_ror:1 row_mask:0xf bank_mask:0xf
	v_add_f32_dpp v201, v201, v201 row_ror:1 row_mask:0xf bank_mask:0xf
	v_mov_b32_e32 v152, v186
	v_mov_b32_e32 v153, v194
	v_cmp_eq_u32_e64 s[52:53], 1, v210
	v_cmp_eq_u32_e64 s[34:35], 2, v210
	v_cmp_eq_u32_e64 s[18:19], 3, v210
	v_cmp_eq_u32_e64 vcc, 4, v210
	v_cndmask_b32_e64 v152, v152, v187, s[52:53]
	v_cndmask_b32_e64 v153, v153, v195, s[52:53]
	v_cndmask_b32_e64 v152, v152, v188, s[34:35]
	v_cndmask_b32_e64 v153, v153, v196, s[34:35]
	v_cndmask_b32_e64 v152, v152, v189, s[18:19]
	v_cndmask_b32_e64 v153, v153, v197, s[18:19]
	v_cndmask_b32_e64 v152, v152, v190, vcc
	v_cndmask_b32_e64 v153, v153, v198, vcc
	v_cmp_eq_u32_e64 s[52:53], 5, v210
	v_cmp_eq_u32_e64 s[34:35], 6, v210
	v_cmp_eq_u32_e64 s[18:19], 7, v210
	s_nop 0
	v_cndmask_b32_e64 v152, v152, v191, s[52:53]
	v_cndmask_b32_e64 v153, v153, v199, s[52:53]
	v_cndmask_b32_e64 v152, v152, v192, s[34:35]
	v_cndmask_b32_e64 v153, v153, v200, s[34:35]
	v_cndmask_b32_e64 v152, v152, v193, s[18:19]
	v_cndmask_b32_e64 v153, v153, v201, s[18:19]
	v_cmp_gt_u32_e64 s[52:53], 8, v210
	s_nop 1
;     __device__ __forceinline__ void operator()(f32x4 (&acc)[2][2][4][2], const Unit& u, int wr, int wc, int fr, int fq) const {
;     ...
; #pragma unroll
;             for (int bj = 0; bj < 2; ++bj) {
;                 const int tok = tok0 + bj * 32;
;                 f32x4 r0, r1;
;                 {
;                     const float* sp = ss + (size_t)(tok + (fr & 7)) * 32 + 16 * (fr >> 3);
;                     const f32x4 a = *(const f32x4*)sp, b = *(const f32x4*)(sp + 4), c = *(const f32x4*)(sp + 8), d = *(const f32x4*)(sp + 12);
;                     float s = (((a[0] + a[1]) + (a[2] + a[3])) + ((b[0] + b[1]) + (b[2] + b[3]))) + (((c[0] + c[1]) + (c[2] + c[3])) + ((d[0] + d[1]) + (d[2] + d[3])));
;                     s += __shfl_xor(s, 8);
;                     const float rt = __builtin_amdgcn_rsqf(s * (1.0f / D) + RMS_EPS);
;                     const int lb = (fq << 4);
; #pragma unroll
;                     for (int j = 0; j < 4; ++j) { r0[j] = __shfl(rt, lb | j); r1[j] = __shfl(rt, lb | (4 + j)); }
;                 }
;                 f32x4 s0 = {0.f, 0.f, 0.f, 0.f}, s1 = s0, q0 = s0, q1 = s0;
; #pragma unroll
;                 for (int ai = 0; ai < 2; ++ai)
; #pragma unroll
;                     for (int m = 0; m < 4; ++m) {
;                         const int ch = ch0 + ai * HALF + m * 16;
;                         f32x4 v0 = acc[ai][bj][m][0] * r0, v1 = acc[ai][bj][m][1] * r1;
;                         if (isg) { v0 = gelu4(v0); v1 = gelu4(v1); s0 += v0; s1 += v1; q0 += v0 * v0; q1 += v1 * v1; }
;                         *(u32x4*)(base + (size_t)ch * T + tok) = pack8(v0, v1);
;                     }
;                 if (isg) {
; #pragma unroll
;                     for (int o = 1; o < 16; o <<= 1) {
; #pragma unroll
;                         for (int j = 0; j < 4; ++j) { s0[j] += __shfl_xor(s0[j], o); s1[j] += __shfl_xor(s1[j], o); q0[j] += __shfl_xor(q0[j], o); q1[j] += __shfl_xor(q1[j], o); }
;                     }
; #pragma unroll
;                     for (int j = 0; j < 4; ++j) {
;                         const int pidx = (u.pn - 4) * 2 + wr;
;                         if (fr == j)     *(f32x2*)(lns + ((size_t)(tok + j) * 8 + pidx) * 2) = (f32x2){s0[j], q0[j]};
;                         if (fr == 4 + j) *(f32x2*)(lns + ((size_t)(tok + 4 + j) * 8 + pidx) * 2) = (f32x2){s1[j], q1[j]};
;                     }
	s_and_saveexec_b64 s[34:35], s[52:53]
	global_store_dwordx2 v162, v[152:153], s[56:57]
	s_mov_b64 exec, s[34:35]
	s_nop 1
	v_mov_b32_dpp v202, v251 row_newbcast:0 row_mask:0xf bank_mask:0xf
	v_mov_b32_dpp v203, v251 row_newbcast:1 row_mask:0xf bank_mask:0xf
	v_mov_b32_dpp v204, v251 row_newbcast:2 row_mask:0xf bank_mask:0xf
	v_mov_b32_dpp v205, v251 row_newbcast:3 row_mask:0xf bank_mask:0xf
	v_mov_b32_dpp v206, v251 row_newbcast:4 row_mask:0xf bank_mask:0xf
	v_mov_b32_dpp v207, v251 row_newbcast:5 row_mask:0xf bank_mask:0xf
	v_mov_b32_dpp v208, v251 row_newbcast:6 row_mask:0xf bank_mask:0xf
	v_mov_b32_dpp v209, v251 row_newbcast:7 row_mask:0xf bank_mask:0xf
	v_mov_b64_e32 v[186:187], 0
	v_mov_b64_e32 v[188:189], 0
	v_mov_b64_e32 v[190:191], 0
	v_mov_b64_e32 v[192:193], 0
	v_mov_b64_e32 v[194:195], 0
	v_mov_b64_e32 v[196:197], 0
	v_mov_b64_e32 v[198:199], 0
	v_mov_b64_e32 v[200:201], 0
	v_pk_mul_f32 v[120:121], v[120:121], v[202:203]
	v_pk_mul_f32 v[122:123], v[122:123], v[204:205]
	v_pk_mul_f32 v[116:117], v[116:117], v[206:207]
	v_pk_mul_f32 v[118:119], v[118:119], v[208:209]
	v_pk_mul_f32 v[218:219], v[120:121], s[38:39]
	v_pk_mul_f32 v[220:221], v[122:123], s[38:39]
	v_pk_mul_f32 v[222:223], v[116:117], s[38:39]
	v_pk_mul_f32 v[224:225], v[118:119], s[38:39]
	v_pk_mul_f32 v[218:219], v[120:121], v[218:219]
	v_pk_mul_f32 v[220:221], v[122:123], v[220:221]
	v_pk_mul_f32 v[222:223], v[116:117], v[222:223]
	v_pk_mul_f32 v[224:225], v[118:119], v[224:225]
	v_pk_fma_f32 v[218:219], v[120:121], v[218:219], v[120:121]
	v_pk_fma_f32 v[220:221], v[122:123], v[220:221], v[122:123]
	v_pk_fma_f32 v[222:223], v[116:117], v[222:223], v[116:117]
	v_pk_fma_f32 v[224:225], v[118:119], v[224:225], v[118:119]
	v_pk_mul_f32 v[218:219], v[218:219], s[40:41]
	v_pk_mul_f32 v[220:221], v[220:221], s[40:41]
	v_pk_mul_f32 v[222:223], v[222:223], s[40:41]
	v_pk_mul_f32 v[224:225], v[224:225], s[40:41]
	v_exp_f32_e32 v218, v218
	v_exp_f32_e32 v219, v219
	v_exp_f32_e32 v220, v220
	v_exp_f32_e32 v221, v221
	v_exp_f32_e32 v222, v222
	v_exp_f32_e32 v223, v223
	v_exp_f32_e32 v224, v224
	v_exp_f32_e32 v225, v225
	v_pk_add_f32 v[218:219], v[218:219], s[42:43]
	v_pk_add_f32 v[220:221], v[220:221], s[42:43]
	v_pk_add_f32 v[222:223], v[222:223], s[42:43]
	v_pk_add_f32 v[224:225], v[224:225], s[42:43]
	v_rcp_f32_e32 v218, v218
	v_rcp_f32_e32 v219, v219
	v_rcp_f32_e32 v220, v220
	v_rcp_f32_e32 v221, v221
	v_rcp_f32_e32 v222, v222
	v_rcp_f32_e32 v223, v223
	v_rcp_f32_e32 v224, v224
	v_rcp_f32_e32 v225, v225
	v_pk_mul_f32 v[218:219], v[120:121], v[218:219]
	v_pk_mul_f32 v[220:221], v[122:123], v[220:221]
	v_pk_mul_f32 v[222:223], v[116:117], v[222:223]
	v_pk_mul_f32 v[224:225], v[118:119], v[224:225]
	v_pk_add_f32 v[186:187], v[186:187], v[218:219]
	v_pk_add_f32 v[188:189], v[188:189], v[220:221]
	v_pk_add_f32 v[190:191], v[190:191], v[222:223]
	v_pk_add_f32 v[192:193], v[192:193], v[224:225]
	v_pk_fma_f32 v[194:195], v[218:219], v[218:219], v[194:195]
	v_pk_fma_f32 v[196:197], v[220:221], v[220:221], v[196:197]
	v_pk_fma_f32 v[198:199], v[222:223], v[222:223], v[198:199]
	v_pk_fma_f32 v[200:201], v[224:225], v[224:225], v[200:201]
	v_cvt_pk_bf16_f32 v226, v218, v219
	v_cvt_pk_bf16_f32 v227, v220, v221
	v_cvt_pk_bf16_f32 v228, v222, v223
	v_cvt_pk_bf16_f32 v229, v224, v225
	global_store_dwordx4 v185, v[226:229], s[12:13] offset:64
	v_pk_mul_f32 v[104:105], v[104:105], v[202:203]
	v_pk_mul_f32 v[106:107], v[106:107], v[204:205]
	v_pk_mul_f32 v[100:101], v[100:101], v[206:207]
	v_pk_mul_f32 v[102:103], v[102:103], v[208:209]
	v_pk_mul_f32 v[218:219], v[104:105], s[38:39]
	v_pk_mul_f32 v[220:221], v[106:107], s[38:39]
	v_pk_mul_f32 v[222:223], v[100:101], s[38:39]
	v_pk_mul_f32 v[224:225], v[102:103], s[38:39]
	v_pk_mul_f32 v[218:219], v[104:105], v[218:219]
	v_pk_mul_f32 v[220:221], v[106:107], v[220:221]
	v_pk_mul_f32 v[222:223], v[100:101], v[222:223]
	v_pk_mul_f32 v[224:225], v[102:103], v[224:225]
	v_pk_fma_f32 v[218:219], v[104:105], v[218:219], v[104:105]
	v_pk_fma_f32 v[220:221], v[106:107], v[220:221], v[106:107]
	v_pk_fma_f32 v[222:223], v[100:101], v[222:223], v[100:101]
	v_pk_fma_f32 v[224:225], v[102:103], v[224:225], v[102:103]
	v_pk_mul_f32 v[218:219], v[218:219], s[40:41]
	v_pk_mul_f32 v[220:221], v[220:221], s[40:41]
	v_pk_mul_f32 v[222:223], v[222:223], s[40:41]
	v_pk_mul_f32 v[224:225], v[224:225], s[40:41]
	v_exp_f32_e32 v218, v218
	v_exp_f32_e32 v219, v219
	v_exp_f32_e32 v220, v220
	v_exp_f32_e32 v221, v221
	v_exp_f32_e32 v222, v222
	v_exp_f32_e32 v223, v223
	v_exp_f32_e32 v224, v224
	v_exp_f32_e32 v225, v225
	v_pk_add_f32 v[218:219], v[218:219], s[42:43]
	v_pk_add_f32 v[220:221], v[220:221], s[42:43]
	v_pk_add_f32 v[222:223], v[222:223], s[42:43]
	v_pk_add_f32 v[224:225], v[224:225], s[42:43]
	v_rcp_f32_e32 v218, v218
	v_rcp_f32_e32 v219, v219
	v_rcp_f32_e32 v220, v220
	v_rcp_f32_e32 v221, v221
	v_rcp_f32_e32 v222, v222
	v_rcp_f32_e32 v223, v223
	v_rcp_f32_e32 v224, v224
	v_rcp_f32_e32 v225, v225
	v_pk_mul_f32 v[218:219], v[104:105], v[218:219]
	v_pk_mul_f32 v[220:221], v[106:107], v[220:221]
	v_pk_mul_f32 v[222:223], v[100:101], v[222:223]
	v_pk_mul_f32 v[224:225], v[102:103], v[224:225]
	v_pk_add_f32 v[186:187], v[186:187], v[218:219]
	v_pk_add_f32 v[188:189], v[188:189], v[220:221]
	v_pk_add_f32 v[190:191], v[190:191], v[222:223]
	v_pk_add_f32 v[192:193], v[192:193], v[224:225]
	v_pk_fma_f32 v[194:195], v[218:219], v[218:219], v[194:195]
	v_pk_fma_f32 v[196:197], v[220:221], v[220:221], v[196:197]
	v_pk_fma_f32 v[198:199], v[222:223], v[222:223], v[198:199]
	v_pk_fma_f32 v[200:201], v[224:225], v[224:225], v[200:201]
	v_cvt_pk_bf16_f32 v132, v218, v219
; __device__ __forceinline__ f32x4 gelu4(f32x4 v) { return (f32x4){gelu_tanh(v[0]), gelu_tanh(v[1]), gelu_tanh(v[2]), gelu_tanh(v[3])}; }
; __device__ __forceinline__ u32x4 pack8(f32x4 a, f32x4 b) { u32x4 w; w.x = cvt_pk_bf16(a[0], a[1]); w.y = cvt_pk_bf16(a[2], a[3]); w.z = cvt_pk_bf16(b[0], b[1]); w.w = cvt_pk_bf16(b[2], b[3]); return w; }
;     __device__ __forceinline__ void operator()(f32x4 (&acc)[2][2][4][2], const Unit& u, int wr, int wc, int fr, int fq) const {
;     ...
;                 for (int ai = 0; ai < 2; ++ai)
; #pragma unroll
;                     for (int m = 0; m < 4; ++m) {
;                         const int ch = ch0 + ai * HALF + m * 16;
;                         f32x4 v0 = acc[ai][bj][m][0] * r0, v1 = acc[ai][bj][m][1] * r1;
;                         if (isg) { v0 = gelu4(v0); v1 = gelu4(v1); s0 += v0; s1 += v1; q0 += v0 * v0; q1 += v1 * v1; }
;                         *(u32x4*)(base + (size_t)ch * T + tok) = pack8(v0, v1);
	v_cvt_pk_bf16_f32 v133, v220, v221
	v_cvt_pk_bf16_f32 v134, v222, v223
	v_cvt_pk_bf16_f32 v135, v224, v225
	v_add_u32_e32 v0, 0x40000, v185
	global_store_dwordx4 v0, v[132:135], s[12:13] offset:64
	v_pk_mul_f32 v[88:89], v[88:89], v[202:203]
	v_pk_mul_f32 v[90:91], v[90:91], v[204:205]
	v_pk_mul_f32 v[84:85], v[84:85], v[206:207]
	v_pk_mul_f32 v[86:87], v[86:87], v[208:209]
	v_pk_mul_f32 v[218:219], v[88:89], s[38:39]
	v_pk_mul_f32 v[220:221], v[90:91], s[38:39]
	v_pk_mul_f32 v[222:223], v[84:85], s[38:39]
	v_pk_mul_f32 v[224:225], v[86:87], s[38:39]
	v_pk_mul_f32 v[218:219], v[88:89], v[218:219]
	v_pk_mul_f32 v[220:221], v[90:91], v[220:221]
	v_pk_mul_f32 v[222:223], v[84:85], v[222:223]
	v_pk_mul_f32 v[224:225], v[86:87], v[224:225]
	v_pk_fma_f32 v[218:219], v[88:89], v[218:219], v[88:89]
	v_pk_fma_f32 v[220:221], v[90:91], v[220:221], v[90:91]
	v_pk_fma_f32 v[222:223], v[84:85], v[222:223], v[84:85]
	v_pk_fma_f32 v[224:225], v[86:87], v[224:225], v[86:87]
	v_pk_mul_f32 v[218:219], v[218:219], s[40:41]
	v_pk_mul_f32 v[220:221], v[220:221], s[40:41]
	v_pk_mul_f32 v[222:223], v[222:223], s[40:41]
	v_pk_mul_f32 v[224:225], v[224:225], s[40:41]
	v_exp_f32_e32 v218, v218
	v_exp_f32_e32 v219, v219
	v_exp_f32_e32 v220, v220
	v_exp_f32_e32 v221, v221
	v_exp_f32_e32 v222, v222
	v_exp_f32_e32 v223, v223
	v_exp_f32_e32 v224, v224
	v_exp_f32_e32 v225, v225
	v_pk_add_f32 v[218:219], v[218:219], s[42:43]
	v_pk_add_f32 v[220:221], v[220:221], s[42:43]
	v_pk_add_f32 v[222:223], v[222:223], s[42:43]
	v_pk_add_f32 v[224:225], v[224:225], s[42:43]
	v_rcp_f32_e32 v218, v218
	v_rcp_f32_e32 v219, v219
	v_rcp_f32_e32 v220, v220
	v_rcp_f32_e32 v221, v221
	v_rcp_f32_e32 v222, v222
	v_rcp_f32_e32 v223, v223
	v_rcp_f32_e32 v224, v224
	v_rcp_f32_e32 v225, v225
	v_pk_mul_f32 v[218:219], v[88:89], v[218:219]
	v_pk_mul_f32 v[220:221], v[90:91], v[220:221]
	v_pk_mul_f32 v[222:223], v[84:85], v[222:223]
	v_pk_mul_f32 v[224:225], v[86:87], v[224:225]
	v_pk_add_f32 v[186:187], v[186:187], v[218:219]
	v_pk_add_f32 v[188:189], v[188:189], v[220:221]
	v_pk_add_f32 v[190:191], v[190:191], v[222:223]
	v_pk_add_f32 v[192:193], v[192:193], v[224:225]
	v_pk_fma_f32 v[194:195], v[218:219], v[218:219], v[194:195]
	v_pk_fma_f32 v[196:197], v[220:221], v[220:221], v[196:197]
	v_pk_fma_f32 v[198:199], v[222:223], v[222:223], v[198:199]
	v_pk_fma_f32 v[200:201], v[224:225], v[224:225], v[200:201]
	v_cvt_pk_bf16_f32 v226, v218, v219
	v_cvt_pk_bf16_f32 v227, v220, v221
	v_cvt_pk_bf16_f32 v228, v222, v223
	v_cvt_pk_bf16_f32 v229, v224, v225
	v_add_u32_e32 v0, 0x80000, v185
	global_store_dwordx4 v0, v[226:229], s[12:13] offset:64
	v_pk_mul_f32 v[72:73], v[72:73], v[202:203]
	v_pk_mul_f32 v[74:75], v[74:75], v[204:205]
	v_pk_mul_f32 v[68:69], v[68:69], v[206:207]
	v_pk_mul_f32 v[70:71], v[70:71], v[208:209]
	v_pk_mul_f32 v[218:219], v[72:73], s[38:39]
	v_pk_mul_f32 v[220:221], v[74:75], s[38:39]
	v_pk_mul_f32 v[222:223], v[68:69], s[38:39]
	v_pk_mul_f32 v[224:225], v[70:71], s[38:39]
	v_pk_mul_f32 v[218:219], v[72:73], v[218:219]
	v_pk_mul_f32 v[220:221], v[74:75], v[220:221]
	v_pk_mul_f32 v[222:223], v[68:69], v[222:223]
	v_pk_mul_f32 v[224:225], v[70:71], v[224:225]
	v_pk_fma_f32 v[218:219], v[72:73], v[218:219], v[72:73]
	v_pk_fma_f32 v[220:221], v[74:75], v[220:221], v[74:75]
	v_pk_fma_f32 v[222:223], v[68:69], v[222:223], v[68:69]
	v_pk_fma_f32 v[224:225], v[70:71], v[224:225], v[70:71]
	v_pk_mul_f32 v[218:219], v[218:219], s[40:41]
	v_pk_mul_f32 v[220:221], v[220:221], s[40:41]
	v_pk_mul_f32 v[222:223], v[222:223], s[40:41]
	v_pk_mul_f32 v[224:225], v[224:225], s[40:41]
	v_exp_f32_e32 v218, v218
	v_exp_f32_e32 v219, v219
	v_exp_f32_e32 v220, v220
	v_exp_f32_e32 v221, v221
	v_exp_f32_e32 v222, v222
	v_exp_f32_e32 v223, v223
	v_exp_f32_e32 v224, v224
	v_exp_f32_e32 v225, v225
	v_pk_add_f32 v[218:219], v[218:219], s[42:43]
	v_pk_add_f32 v[220:221], v[220:221], s[42:43]
	v_pk_add_f32 v[222:223], v[222:223], s[42:43]
	v_pk_add_f32 v[224:225], v[224:225], s[42:43]
	v_rcp_f32_e32 v218, v218
	v_rcp_f32_e32 v219, v219
	v_rcp_f32_e32 v220, v220
	v_rcp_f32_e32 v221, v221
	v_rcp_f32_e32 v222, v222
	v_rcp_f32_e32 v223, v223
	v_rcp_f32_e32 v224, v224
	v_rcp_f32_e32 v225, v225
	v_pk_mul_f32 v[218:219], v[72:73], v[218:219]
	v_pk_mul_f32 v[220:221], v[74:75], v[220:221]
	v_pk_mul_f32 v[222:223], v[68:69], v[222:223]
	v_pk_mul_f32 v[224:225], v[70:71], v[224:225]
	v_pk_add_f32 v[186:187], v[186:187], v[218:219]
	v_pk_add_f32 v[188:189], v[188:189], v[220:221]
	v_pk_add_f32 v[190:191], v[190:191], v[222:223]
	v_pk_add_f32 v[192:193], v[192:193], v[224:225]
	v_pk_fma_f32 v[194:195], v[218:219], v[218:219], v[194:195]
	v_pk_fma_f32 v[196:197], v[220:221], v[220:221], v[196:197]
	v_pk_fma_f32 v[198:199], v[222:223], v[222:223], v[198:199]
	v_pk_fma_f32 v[200:201], v[224:225], v[224:225], v[200:201]
	v_cvt_pk_bf16_f32 v132, v218, v219
	v_cvt_pk_bf16_f32 v133, v220, v221
	v_cvt_pk_bf16_f32 v134, v222, v223
	v_cvt_pk_bf16_f32 v135, v224, v225
	v_add_u32_e32 v0, 0xc0000, v185
	global_store_dwordx4 v0, v[132:135], s[12:13] offset:64
	v_pk_mul_f32 v[56:57], v[56:57], v[202:203]
	v_pk_mul_f32 v[58:59], v[58:59], v[204:205]
	v_pk_mul_f32 v[52:53], v[52:53], v[206:207]
	v_pk_mul_f32 v[54:55], v[54:55], v[208:209]
	v_pk_mul_f32 v[218:219], v[56:57], s[38:39]
	v_pk_mul_f32 v[220:221], v[58:59], s[38:39]
	v_pk_mul_f32 v[222:223], v[52:53], s[38:39]
	v_pk_mul_f32 v[224:225], v[54:55], s[38:39]
	v_pk_mul_f32 v[218:219], v[56:57], v[218:219]
	v_pk_mul_f32 v[220:221], v[58:59], v[220:221]
	v_pk_mul_f32 v[222:223], v[52:53], v[222:223]
	v_pk_mul_f32 v[224:225], v[54:55], v[224:225]
	v_pk_fma_f32 v[218:219], v[56:57], v[218:219], v[56:57]
; __device__ __forceinline__ f32x4 gelu4(f32x4 v) { return (f32x4){gelu_tanh(v[0]), gelu_tanh(v[1]), gelu_tanh(v[2]), gelu_tanh(v[3])}; }
; __device__ __forceinline__ u32x4 pack8(f32x4 a, f32x4 b) { u32x4 w; w.x = cvt_pk_bf16(a[0], a[1]); w.y = cvt_pk_bf16(a[2], a[3]); w.z = cvt_pk_bf16(b[0], b[1]); w.w = cvt_pk_bf16(b[2], b[3]); return w; }
;     __device__ __forceinline__ void operator()(f32x4 (&acc)[2][2][4][2], const Unit& u, int wr, int wc, int fr, int fq) const {
;     ...
;                 for (int ai = 0; ai < 2; ++ai)
; #pragma unroll
;                     for (int m = 0; m < 4; ++m) {
;                         const int ch = ch0 + ai * HALF + m * 16;
;                         f32x4 v0 = acc[ai][bj][m][0] * r0, v1 = acc[ai][bj][m][1] * r1;
;                         if (isg) { v0 = gelu4(v0); v1 = gelu4(v1); s0 += v0; s1 += v1; q0 += v0 * v0; q1 += v1 * v1; }
;                         *(u32x4*)(base + (size_t)ch * T + tok) = pack8(v0, v1);
	v_pk_fma_f32 v[220:221], v[58:59], v[220:221], v[58:59]
	v_pk_fma_f32 v[222:223], v[52:53], v[222:223], v[52:53]
	v_pk_fma_f32 v[224:225], v[54:55], v[224:225], v[54:55]
	v_pk_mul_f32 v[218:219], v[218:219], s[40:41]
	v_pk_mul_f32 v[220:221], v[220:221], s[40:41]
	v_pk_mul_f32 v[222:223], v[222:223], s[40:41]
	v_pk_mul_f32 v[224:225], v[224:225], s[40:41]
	v_exp_f32_e32 v218, v218
	v_exp_f32_e32 v219, v219
	v_exp_f32_e32 v220, v220
	v_exp_f32_e32 v221, v221
	v_exp_f32_e32 v222, v222
	v_exp_f32_e32 v223, v223
	v_exp_f32_e32 v224, v224
	v_exp_f32_e32 v225, v225
	v_pk_add_f32 v[218:219], v[218:219], s[42:43]
	v_pk_add_f32 v[220:221], v[220:221], s[42:43]
	v_pk_add_f32 v[222:223], v[222:223], s[42:43]
	v_pk_add_f32 v[224:225], v[224:225], s[42:43]
	v_rcp_f32_e32 v218, v218
	v_rcp_f32_e32 v219, v219
	v_rcp_f32_e32 v220, v220
	v_rcp_f32_e32 v221, v221
	v_rcp_f32_e32 v222, v222
	v_rcp_f32_e32 v223, v223
	v_rcp_f32_e32 v224, v224
	v_rcp_f32_e32 v225, v225
	v_pk_mul_f32 v[218:219], v[56:57], v[218:219]
	v_pk_mul_f32 v[220:221], v[58:59], v[220:221]
	v_pk_mul_f32 v[222:223], v[52:53], v[222:223]
	v_pk_mul_f32 v[224:225], v[54:55], v[224:225]
	v_pk_add_f32 v[186:187], v[186:187], v[218:219]
	v_pk_add_f32 v[188:189], v[188:189], v[220:221]
	v_pk_add_f32 v[190:191], v[190:191], v[222:223]
	v_pk_add_f32 v[192:193], v[192:193], v[224:225]
	v_pk_fma_f32 v[194:195], v[218:219], v[218:219], v[194:195]
	v_pk_fma_f32 v[196:197], v[220:221], v[220:221], v[196:197]
	v_pk_fma_f32 v[198:199], v[222:223], v[222:223], v[198:199]
	v_pk_fma_f32 v[200:201], v[224:225], v[224:225], v[200:201]
	v_cvt_pk_bf16_f32 v226, v218, v219
	v_cvt_pk_bf16_f32 v227, v220, v221
	v_cvt_pk_bf16_f32 v228, v222, v223
	v_cvt_pk_bf16_f32 v229, v224, v225
	v_add_u32_e32 v0, 0x200000, v185
	global_store_dwordx4 v0, v[226:229], s[12:13] offset:64
	v_pk_mul_f32 v[40:41], v[40:41], v[202:203]
	v_pk_mul_f32 v[42:43], v[42:43], v[204:205]
	v_pk_mul_f32 v[36:37], v[36:37], v[206:207]
	v_pk_mul_f32 v[38:39], v[38:39], v[208:209]
	v_pk_mul_f32 v[218:219], v[40:41], s[38:39]
	v_pk_mul_f32 v[220:221], v[42:43], s[38:39]
	v_pk_mul_f32 v[222:223], v[36:37], s[38:39]
	v_pk_mul_f32 v[224:225], v[38:39], s[38:39]
	v_pk_mul_f32 v[218:219], v[40:41], v[218:219]
	v_pk_mul_f32 v[220:221], v[42:43], v[220:221]
	v_pk_mul_f32 v[222:223], v[36:37], v[222:223]
	v_pk_mul_f32 v[224:225], v[38:39], v[224:225]
	v_pk_fma_f32 v[218:219], v[40:41], v[218:219], v[40:41]
	v_pk_fma_f32 v[220:221], v[42:43], v[220:221], v[42:43]
	v_pk_fma_f32 v[222:223], v[36:37], v[222:223], v[36:37]
	v_pk_fma_f32 v[224:225], v[38:39], v[224:225], v[38:39]
	v_pk_mul_f32 v[218:219], v[218:219], s[40:41]
	v_pk_mul_f32 v[220:221], v[220:221], s[40:41]
	v_pk_mul_f32 v[222:223], v[222:223], s[40:41]
	v_pk_mul_f32 v[224:225], v[224:225], s[40:41]
	v_exp_f32_e32 v218, v218
	v_exp_f32_e32 v219, v219
	v_exp_f32_e32 v220, v220
	v_exp_f32_e32 v221, v221
	v_exp_f32_e32 v222, v222
	v_exp_f32_e32 v223, v223
	v_exp_f32_e32 v224, v224
	v_exp_f32_e32 v225, v225
	v_pk_add_f32 v[218:219], v[218:219], s[42:43]
	v_pk_add_f32 v[220:221], v[220:221], s[42:43]
	v_pk_add_f32 v[222:223], v[222:223], s[42:43]
	v_pk_add_f32 v[224:225], v[224:225], s[42:43]
	v_rcp_f32_e32 v218, v218
	v_rcp_f32_e32 v219, v219
	v_rcp_f32_e32 v220, v220
	v_rcp_f32_e32 v221, v221
	v_rcp_f32_e32 v222, v222
	v_rcp_f32_e32 v223, v223
	v_rcp_f32_e32 v224, v224
	v_rcp_f32_e32 v225, v225
	v_pk_mul_f32 v[218:219], v[40:41], v[218:219]
	v_pk_mul_f32 v[220:221], v[42:43], v[220:221]
	v_pk_mul_f32 v[222:223], v[36:37], v[222:223]
	v_pk_mul_f32 v[224:225], v[38:39], v[224:225]
	v_pk_add_f32 v[186:187], v[186:187], v[218:219]
	v_pk_add_f32 v[188:189], v[188:189], v[220:221]
	v_pk_add_f32 v[190:191], v[190:191], v[222:223]
	v_pk_add_f32 v[192:193], v[192:193], v[224:225]
	v_pk_fma_f32 v[194:195], v[218:219], v[218:219], v[194:195]
	v_pk_fma_f32 v[196:197], v[220:221], v[220:221], v[196:197]
	v_pk_fma_f32 v[198:199], v[222:223], v[222:223], v[198:199]
	v_pk_fma_f32 v[200:201], v[224:225], v[224:225], v[200:201]
	v_cvt_pk_bf16_f32 v132, v218, v219
	v_cvt_pk_bf16_f32 v133, v220, v221
	v_cvt_pk_bf16_f32 v134, v222, v223
	v_cvt_pk_bf16_f32 v135, v224, v225
	v_add_u32_e32 v0, 0x240000, v185
	global_store_dwordx4 v0, v[132:135], s[12:13] offset:64
	v_pk_mul_f32 v[24:25], v[24:25], v[202:203]
	v_pk_mul_f32 v[26:27], v[26:27], v[204:205]
	v_pk_mul_f32 v[20:21], v[20:21], v[206:207]
	v_pk_mul_f32 v[22:23], v[22:23], v[208:209]
	v_pk_mul_f32 v[218:219], v[24:25], s[38:39]
	v_pk_mul_f32 v[220:221], v[26:27], s[38:39]
	v_pk_mul_f32 v[222:223], v[20:21], s[38:39]
	v_pk_mul_f32 v[224:225], v[22:23], s[38:39]
	v_pk_mul_f32 v[218:219], v[24:25], v[218:219]
	v_pk_mul_f32 v[220:221], v[26:27], v[220:221]
	v_pk_mul_f32 v[222:223], v[20:21], v[222:223]
	v_pk_mul_f32 v[224:225], v[22:23], v[224:225]
	v_pk_fma_f32 v[218:219], v[24:25], v[218:219], v[24:25]
	v_pk_fma_f32 v[220:221], v[26:27], v[220:221], v[26:27]
	v_pk_fma_f32 v[222:223], v[20:21], v[222:223], v[20:21]
	v_pk_fma_f32 v[224:225], v[22:23], v[224:225], v[22:23]
	v_pk_mul_f32 v[218:219], v[218:219], s[40:41]
	v_pk_mul_f32 v[220:221], v[220:221], s[40:41]
	v_pk_mul_f32 v[222:223], v[222:223], s[40:41]
	v_pk_mul_f32 v[224:225], v[224:225], s[40:41]
	v_exp_f32_e32 v218, v218
	v_exp_f32_e32 v219, v219
	v_exp_f32_e32 v220, v220
	v_exp_f32_e32 v221, v221
	v_exp_f32_e32 v222, v222
	v_exp_f32_e32 v223, v223
	v_exp_f32_e32 v224, v224
	v_exp_f32_e32 v225, v225
	v_pk_add_f32 v[218:219], v[218:219], s[42:43]
	v_pk_add_f32 v[220:221], v[220:221], s[42:43]
	v_pk_add_f32 v[222:223], v[222:223], s[42:43]
	v_pk_add_f32 v[224:225], v[224:225], s[42:43]
	v_rcp_f32_e32 v218, v218
; __device__ __forceinline__ f32x4 gelu4(f32x4 v) { return (f32x4){gelu_tanh(v[0]), gelu_tanh(v[1]), gelu_tanh(v[2]), gelu_tanh(v[3])}; }
; __device__ __forceinline__ u32x4 pack8(f32x4 a, f32x4 b) { u32x4 w; w.x = cvt_pk_bf16(a[0], a[1]); w.y = cvt_pk_bf16(a[2], a[3]); w.z = cvt_pk_bf16(b[0], b[1]); w.w = cvt_pk_bf16(b[2], b[3]); return w; }
;     __device__ __forceinline__ void operator()(f32x4 (&acc)[2][2][4][2], const Unit& u, int wr, int wc, int fr, int fq) const {
;     ...
;                 for (int ai = 0; ai < 2; ++ai)
; #pragma unroll
;                     for (int m = 0; m < 4; ++m) {
;                         const int ch = ch0 + ai * HALF + m * 16;
;                         f32x4 v0 = acc[ai][bj][m][0] * r0, v1 = acc[ai][bj][m][1] * r1;
;                         if (isg) { v0 = gelu4(v0); v1 = gelu4(v1); s0 += v0; s1 += v1; q0 += v0 * v0; q1 += v1 * v1; }
;                         *(u32x4*)(base + (size_t)ch * T + tok) = pack8(v0, v1);
;                     }
;                 if (isg) {
; #pragma unroll
;                     for (int o = 1; o < 16; o <<= 1) {
; #pragma unroll
;                         for (int j = 0; j < 4; ++j) { s0[j] += __shfl_xor(s0[j], o); s1[j] += __shfl_xor(s1[j], o); q0[j] += __shfl_xor(q0[j], o); q1[j] += __shfl_xor(q1[j], o); }
;                     }
	v_rcp_f32_e32 v219, v219
	v_rcp_f32_e32 v220, v220
	v_rcp_f32_e32 v221, v221
	v_rcp_f32_e32 v222, v222
	v_rcp_f32_e32 v223, v223
	v_rcp_f32_e32 v224, v224
	v_rcp_f32_e32 v225, v225
	v_pk_mul_f32 v[218:219], v[24:25], v[218:219]
	v_pk_mul_f32 v[220:221], v[26:27], v[220:221]
	v_pk_mul_f32 v[222:223], v[20:21], v[222:223]
	v_pk_mul_f32 v[224:225], v[22:23], v[224:225]
	v_pk_add_f32 v[186:187], v[186:187], v[218:219]
	v_pk_add_f32 v[188:189], v[188:189], v[220:221]
	v_pk_add_f32 v[190:191], v[190:191], v[222:223]
	v_pk_add_f32 v[192:193], v[192:193], v[224:225]
	v_pk_fma_f32 v[194:195], v[218:219], v[218:219], v[194:195]
	v_pk_fma_f32 v[196:197], v[220:221], v[220:221], v[196:197]
	v_pk_fma_f32 v[198:199], v[222:223], v[222:223], v[198:199]
	v_pk_fma_f32 v[200:201], v[224:225], v[224:225], v[200:201]
	v_cvt_pk_bf16_f32 v226, v218, v219
	v_cvt_pk_bf16_f32 v227, v220, v221
	v_cvt_pk_bf16_f32 v228, v222, v223
	v_cvt_pk_bf16_f32 v229, v224, v225
	v_add_u32_e32 v0, 0x280000, v185
	global_store_dwordx4 v0, v[226:229], s[12:13] offset:64
	v_pk_mul_f32 v[8:9], v[8:9], v[202:203]
	v_pk_mul_f32 v[10:11], v[10:11], v[204:205]
	v_pk_mul_f32 v[4:5], v[4:5], v[206:207]
	v_pk_mul_f32 v[6:7], v[6:7], v[208:209]
	v_pk_mul_f32 v[218:219], v[8:9], s[38:39]
	v_pk_mul_f32 v[220:221], v[10:11], s[38:39]
	v_pk_mul_f32 v[222:223], v[4:5], s[38:39]
	v_pk_mul_f32 v[224:225], v[6:7], s[38:39]
	v_pk_mul_f32 v[218:219], v[8:9], v[218:219]
	v_pk_mul_f32 v[220:221], v[10:11], v[220:221]
	v_pk_mul_f32 v[222:223], v[4:5], v[222:223]
	v_pk_mul_f32 v[224:225], v[6:7], v[224:225]
	v_pk_fma_f32 v[218:219], v[8:9], v[218:219], v[8:9]
	v_pk_fma_f32 v[220:221], v[10:11], v[220:221], v[10:11]
	v_pk_fma_f32 v[222:223], v[4:5], v[222:223], v[4:5]
	v_pk_fma_f32 v[224:225], v[6:7], v[224:225], v[6:7]
	v_pk_mul_f32 v[218:219], v[218:219], s[40:41]
	v_pk_mul_f32 v[220:221], v[220:221], s[40:41]
	v_pk_mul_f32 v[222:223], v[222:223], s[40:41]
	v_pk_mul_f32 v[224:225], v[224:225], s[40:41]
	v_exp_f32_e32 v218, v218
	v_exp_f32_e32 v219, v219
	v_exp_f32_e32 v220, v220
	v_exp_f32_e32 v221, v221
	v_exp_f32_e32 v222, v222
	v_exp_f32_e32 v223, v223
	v_exp_f32_e32 v224, v224
	v_exp_f32_e32 v225, v225
	v_pk_add_f32 v[218:219], v[218:219], s[42:43]
	v_pk_add_f32 v[220:221], v[220:221], s[42:43]
	v_pk_add_f32 v[222:223], v[222:223], s[42:43]
	v_pk_add_f32 v[224:225], v[224:225], s[42:43]
	v_rcp_f32_e32 v218, v218
	v_rcp_f32_e32 v219, v219
	v_rcp_f32_e32 v220, v220
	v_rcp_f32_e32 v221, v221
	v_rcp_f32_e32 v222, v222
	v_rcp_f32_e32 v223, v223
	v_rcp_f32_e32 v224, v224
	v_rcp_f32_e32 v225, v225
	v_pk_mul_f32 v[218:219], v[8:9], v[218:219]
	v_pk_mul_f32 v[220:221], v[10:11], v[220:221]
	v_pk_mul_f32 v[222:223], v[4:5], v[222:223]
	v_pk_mul_f32 v[224:225], v[6:7], v[224:225]
	v_pk_add_f32 v[186:187], v[186:187], v[218:219]
	v_pk_add_f32 v[188:189], v[188:189], v[220:221]
	v_pk_add_f32 v[190:191], v[190:191], v[222:223]
	v_pk_add_f32 v[192:193], v[192:193], v[224:225]
	v_pk_fma_f32 v[194:195], v[218:219], v[218:219], v[194:195]
	v_pk_fma_f32 v[196:197], v[220:221], v[220:221], v[196:197]
	v_pk_fma_f32 v[198:199], v[222:223], v[222:223], v[198:199]
	v_pk_fma_f32 v[200:201], v[224:225], v[224:225], v[200:201]
	v_cvt_pk_bf16_f32 v132, v218, v219
	v_cvt_pk_bf16_f32 v133, v220, v221
	v_cvt_pk_bf16_f32 v134, v222, v223
	v_cvt_pk_bf16_f32 v135, v224, v225
	v_add_u32_e32 v0, 0x2c0000, v185
	global_store_dwordx4 v0, v[132:135], s[12:13] offset:64
	v_add_f32_dpp v186, v186, v186 row_ror:8 row_mask:0xf bank_mask:0xf
	v_add_f32_dpp v187, v187, v187 row_ror:8 row_mask:0xf bank_mask:0xf
	v_add_f32_dpp v188, v188, v188 row_ror:8 row_mask:0xf bank_mask:0xf
	v_add_f32_dpp v189, v189, v189 row_ror:8 row_mask:0xf bank_mask:0xf
	v_add_f32_dpp v190, v190, v190 row_ror:8 row_mask:0xf bank_mask:0xf
	v_add_f32_dpp v191, v191, v191 row_ror:8 row_mask:0xf bank_mask:0xf
	v_add_f32_dpp v192, v192, v192 row_ror:8 row_mask:0xf bank_mask:0xf
	v_add_f32_dpp v193, v193, v193 row_ror:8 row_mask:0xf bank_mask:0xf
	v_add_f32_dpp v194, v194, v194 row_ror:8 row_mask:0xf bank_mask:0xf
	v_add_f32_dpp v195, v195, v195 row_ror:8 row_mask:0xf bank_mask:0xf
	v_add_f32_dpp v196, v196, v196 row_ror:8 row_mask:0xf bank_mask:0xf
	v_add_f32_dpp v197, v197, v197 row_ror:8 row_mask:0xf bank_mask:0xf
	v_add_f32_dpp v198, v198, v198 row_ror:8 row_mask:0xf bank_mask:0xf
	v_add_f32_dpp v199, v199, v199 row_ror:8 row_mask:0xf bank_mask:0xf
	v_add_f32_dpp v200, v200, v200 row_ror:8 row_mask:0xf bank_mask:0xf
	v_add_f32_dpp v201, v201, v201 row_ror:8 row_mask:0xf bank_mask:0xf
	v_add_f32_dpp v186, v186, v186 row_ror:4 row_mask:0xf bank_mask:0xf
	v_add_f32_dpp v187, v187, v187 row_ror:4 row_mask:0xf bank_mask:0xf
	v_add_f32_dpp v188, v188, v188 row_ror:4 row_mask:0xf bank_mask:0xf
	v_add_f32_dpp v189, v189, v189 row_ror:4 row_mask:0xf bank_mask:0xf
	v_add_f32_dpp v190, v190, v190 row_ror:4 row_mask:0xf bank_mask:0xf
	v_add_f32_dpp v191, v191, v191 row_ror:4 row_mask:0xf bank_mask:0xf
	v_add_f32_dpp v192, v192, v192 row_ror:4 row_mask:0xf bank_mask:0xf
	v_add_f32_dpp v193, v193, v193 row_ror:4 row_mask:0xf bank_mask:0xf
	v_add_f32_dpp v194, v194, v194 row_ror:4 row_mask:0xf bank_mask:0xf
	v_add_f32_dpp v195, v195, v195 row_ror:4 row_mask:0xf bank_mask:0xf
	v_add_f32_dpp v196, v196, v196 row_ror:4 row_mask:0xf bank_mask:0xf
	v_add_f32_dpp v197, v197, v197 row_ror:4 row_mask:0xf bank_mask:0xf
	v_add_f32_dpp v198, v198, v198 row_ror:4 row_mask:0xf bank_mask:0xf
	v_add_f32_dpp v199, v199, v199 row_ror:4 row_mask:0xf bank_mask:0xf
	v_add_f32_dpp v200, v200, v200 row_ror:4 row_mask:0xf bank_mask:0xf
	v_add_f32_dpp v201, v201, v201 row_ror:4 row_mask:0xf bank_mask:0xf
; __device__ __forceinline__ f32x4 gelu4(f32x4 v) { return (f32x4){gelu_tanh(v[0]), gelu_tanh(v[1]), gelu_tanh(v[2]), gelu_tanh(v[3])}; }
; __device__ __forceinline__ u32x4 pack8(f32x4 a, f32x4 b) { u32x4 w; w.x = cvt_pk_bf16(a[0], a[1]); w.y = cvt_pk_bf16(a[2], a[3]); w.z = cvt_pk_bf16(b[0], b[1]); w.w = cvt_pk_bf16(b[2], b[3]); return w; }
;     __device__ __forceinline__ void operator()(f32x4 (&acc)[2][2][4][2], const Unit& u, int wr, int wc, int fr, int fq) const {
;     ...
;                     const float rt = __builtin_amdgcn_rsqf(s * (1.0f / D) + RMS_EPS);
;                     const int lb = (fq << 4);
; #pragma unroll
;                     for (int j = 0; j < 4; ++j) { r0[j] = __shfl(rt, lb | j); r1[j] = __shfl(rt, lb | (4 + j)); }
;                 }
;                 f32x4 s0 = {0.f, 0.f, 0.f, 0.f}, s1 = s0, q0 = s0, q1 = s0;
; #pragma unroll
;                 for (int ai = 0; ai < 2; ++ai)
; #pragma unroll
;                     for (int m = 0; m < 4; ++m) {
;                         const int ch = ch0 + ai * HALF + m * 16;
;                         f32x4 v0 = acc[ai][bj][m][0] * r0, v1 = acc[ai][bj][m][1] * r1;
;                         if (isg) { v0 = gelu4(v0); v1 = gelu4(v1); s0 += v0; s1 += v1; q0 += v0 * v0; q1 += v1 * v1; }
;                         *(u32x4*)(base + (size_t)ch * T + tok) = pack8(v0, v1);
;                     }
;                 if (isg) {
; #pragma unroll
;                     for (int o = 1; o < 16; o <<= 1) {
; #pragma unroll
;                         for (int j = 0; j < 4; ++j) { s0[j] += __shfl_xor(s0[j], o); s1[j] += __shfl_xor(s1[j], o); q0[j] += __shfl_xor(q0[j], o); q1[j] += __shfl_xor(q1[j], o); }
;                     }
; #pragma unroll
;                     for (int j = 0; j < 4; ++j) {
;                         const int pidx = (u.pn - 4) * 2 + wr;
;                         if (fr == j)     *(f32x2*)(lns + ((size_t)(tok + j) * 8 + pidx) * 2) = (f32x2){s0[j], q0[j]};
;                         if (fr == 4 + j) *(f32x2*)(lns + ((size_t)(tok + 4 + j) * 8 + pidx) * 2) = (f32x2){s1[j], q1[j]};
;                     }
	v_add_f32_dpp v186, v186, v186 row_ror:2 row_mask:0xf bank_mask:0xf
	v_add_f32_dpp v187, v187, v187 row_ror:2 row_mask:0xf bank_mask:0xf
	v_add_f32_dpp v188, v188, v188 row_ror:2 row_mask:0xf bank_mask:0xf
	v_add_f32_dpp v189, v189, v189 row_ror:2 row_mask:0xf bank_mask:0xf
	v_add_f32_dpp v190, v190, v190 row_ror:2 row_mask:0xf bank_mask:0xf
	v_add_f32_dpp v191, v191, v191 row_ror:2 row_mask:0xf bank_mask:0xf
	v_add_f32_dpp v192, v192, v192 row_ror:2 row_mask:0xf bank_mask:0xf
	v_add_f32_dpp v193, v193, v193 row_ror:2 row_mask:0xf bank_mask:0xf
	v_add_f32_dpp v194, v194, v194 row_ror:2 row_mask:0xf bank_mask:0xf
	v_add_f32_dpp v195, v195, v195 row_ror:2 row_mask:0xf bank_mask:0xf
	v_add_f32_dpp v196, v196, v196 row_ror:2 row_mask:0xf bank_mask:0xf
	v_add_f32_dpp v197, v197, v197 row_ror:2 row_mask:0xf bank_mask:0xf
	v_add_f32_dpp v198, v198, v198 row_ror:2 row_mask:0xf bank_mask:0xf
	v_add_f32_dpp v199, v199, v199 row_ror:2 row_mask:0xf bank_mask:0xf
	v_add_f32_dpp v200, v200, v200 row_ror:2 row_mask:0xf bank_mask:0xf
	v_add_f32_dpp v201, v201, v201 row_ror:2 row_mask:0xf bank_mask:0xf
	v_add_f32_dpp v186, v186, v186 row_ror:1 row_mask:0xf bank_mask:0xf
	v_add_f32_dpp v187, v187, v187 row_ror:1 row_mask:0xf bank_mask:0xf
	v_add_f32_dpp v188, v188, v188 row_ror:1 row_mask:0xf bank_mask:0xf
	v_add_f32_dpp v189, v189, v189 row_ror:1 row_mask:0xf bank_mask:0xf
	v_add_f32_dpp v190, v190, v190 row_ror:1 row_mask:0xf bank_mask:0xf
	v_add_f32_dpp v191, v191, v191 row_ror:1 row_mask:0xf bank_mask:0xf
	v_add_f32_dpp v192, v192, v192 row_ror:1 row_mask:0xf bank_mask:0xf
	v_add_f32_dpp v193, v193, v193 row_ror:1 row_mask:0xf bank_mask:0xf
	v_add_f32_dpp v194, v194, v194 row_ror:1 row_mask:0xf bank_mask:0xf
	v_add_f32_dpp v195, v195, v195 row_ror:1 row_mask:0xf bank_mask:0xf
	v_add_f32_dpp v196, v196, v196 row_ror:1 row_mask:0xf bank_mask:0xf
	v_add_f32_dpp v197, v197, v197 row_ror:1 row_mask:0xf bank_mask:0xf
	v_add_f32_dpp v198, v198, v198 row_ror:1 row_mask:0xf bank_mask:0xf
	v_add_f32_dpp v199, v199, v199 row_ror:1 row_mask:0xf bank_mask:0xf
	v_add_f32_dpp v200, v200, v200 row_ror:1 row_mask:0xf bank_mask:0xf
	v_add_f32_dpp v201, v201, v201 row_ror:1 row_mask:0xf bank_mask:0xf
	v_mov_b32_e32 v152, v186
	v_mov_b32_e32 v153, v194
	v_cmp_eq_u32_e64 s[52:53], 1, v210
	v_cmp_eq_u32_e64 s[34:35], 2, v210
	v_cmp_eq_u32_e64 s[18:19], 3, v210
	v_cmp_eq_u32_e64 vcc, 4, v210
	v_cndmask_b32_e64 v152, v152, v187, s[52:53]
	v_cndmask_b32_e64 v153, v153, v195, s[52:53]
	v_cndmask_b32_e64 v152, v152, v188, s[34:35]
	v_cndmask_b32_e64 v153, v153, v196, s[34:35]
	v_cndmask_b32_e64 v152, v152, v189, s[18:19]
	v_cndmask_b32_e64 v153, v153, v197, s[18:19]
	v_cndmask_b32_e64 v152, v152, v190, vcc
	v_cndmask_b32_e64 v153, v153, v198, vcc
	v_cmp_eq_u32_e64 s[52:53], 5, v210
	v_cmp_eq_u32_e64 s[34:35], 6, v210
	v_cmp_eq_u32_e64 s[18:19], 7, v210
	s_nop 0
	v_cndmask_b32_e64 v152, v152, v191, s[52:53]
	v_cndmask_b32_e64 v153, v153, v199, s[52:53]
	v_cndmask_b32_e64 v152, v152, v192, s[34:35]
	v_cndmask_b32_e64 v153, v153, v200, s[34:35]
	v_cndmask_b32_e64 v152, v152, v193, s[18:19]
	v_cndmask_b32_e64 v153, v153, v201, s[18:19]
	v_cmp_gt_u32_e64 s[52:53], 8, v210
	s_nop 1
	s_and_saveexec_b64 s[34:35], s[52:53]
	global_store_dwordx2 v162, v[152:153], s[56:57] offset:2048
	s_mov_b64 exec, s[34:35]
	s_branch .LBB0_354
.Lp1t_plain:
	s_nop 1
	v_mov_b32_dpp v202, v250 row_newbcast:0 row_mask:0xf bank_mask:0xf
	v_mov_b32_dpp v203, v250 row_newbcast:1 row_mask:0xf bank_mask:0xf
	v_mov_b32_dpp v204, v250 row_newbcast:2 row_mask:0xf bank_mask:0xf
	v_mov_b32_dpp v205, v250 row_newbcast:3 row_mask:0xf bank_mask:0xf
	v_mov_b32_dpp v206, v250 row_newbcast:4 row_mask:0xf bank_mask:0xf
	v_mov_b32_dpp v207, v250 row_newbcast:5 row_mask:0xf bank_mask:0xf
	v_mov_b32_dpp v208, v250 row_newbcast:6 row_mask:0xf bank_mask:0xf
	v_mov_b32_dpp v209, v250 row_newbcast:7 row_mask:0xf bank_mask:0xf
	v_pk_mul_f32 v[128:129], v[128:129], v[202:203]
	v_pk_mul_f32 v[130:131], v[130:131], v[204:205]
	v_pk_mul_f32 v[124:125], v[124:125], v[206:207]
	v_pk_mul_f32 v[126:127], v[126:127], v[208:209]
	v_cvt_pk_bf16_f32 v226, v128, v129
	v_cvt_pk_bf16_f32 v227, v130, v131
	v_cvt_pk_bf16_f32 v228, v124, v125
	v_cvt_pk_bf16_f32 v229, v126, v127
	global_store_dwordx4 v185, v[226:229], s[12:13]
	v_pk_mul_f32 v[112:113], v[112:113], v[202:203]
	v_pk_mul_f32 v[114:115], v[114:115], v[204:205]
	v_pk_mul_f32 v[108:109], v[108:109], v[206:207]
	v_pk_mul_f32 v[110:111], v[110:111], v[208:209]
	v_cvt_pk_bf16_f32 v132, v112, v113
	v_cvt_pk_bf16_f32 v133, v114, v115
	v_cvt_pk_bf16_f32 v134, v108, v109
	v_cvt_pk_bf16_f32 v135, v110, v111
	v_add_u32_e32 v0, 0x40000, v185
	global_store_dwordx4 v0, v[132:135], s[12:13]
	v_pk_mul_f32 v[96:97], v[96:97], v[202:203]
	v_pk_mul_f32 v[98:99], v[98:99], v[204:205]
	v_pk_mul_f32 v[92:93], v[92:93], v[206:207]
	v_pk_mul_f32 v[94:95], v[94:95], v[208:209]
	v_cvt_pk_bf16_f32 v226, v96, v97
	v_cvt_pk_bf16_f32 v227, v98, v99
	v_cvt_pk_bf16_f32 v228, v92, v93
	v_cvt_pk_bf16_f32 v229, v94, v95
	v_add_u32_e32 v0, 0x80000, v185
	global_store_dwordx4 v0, v[226:229], s[12:13]
	v_pk_mul_f32 v[80:81], v[80:81], v[202:203]
	v_pk_mul_f32 v[82:83], v[82:83], v[204:205]
	v_pk_mul_f32 v[76:77], v[76:77], v[206:207]
	v_pk_mul_f32 v[78:79], v[78:79], v[208:209]
	v_cvt_pk_bf16_f32 v132, v80, v81
	v_cvt_pk_bf16_f32 v133, v82, v83
	v_cvt_pk_bf16_f32 v134, v76, v77
	v_cvt_pk_bf16_f32 v135, v78, v79
	v_add_u32_e32 v0, 0xc0000, v185
; __device__ __forceinline__ f32x4 gelu4(f32x4 v) { return (f32x4){gelu_tanh(v[0]), gelu_tanh(v[1]), gelu_tanh(v[2]), gelu_tanh(v[3])}; }
; __device__ __forceinline__ u32x4 pack8(f32x4 a, f32x4 b) { u32x4 w; w.x = cvt_pk_bf16(a[0], a[1]); w.y = cvt_pk_bf16(a[2], a[3]); w.z = cvt_pk_bf16(b[0], b[1]); w.w = cvt_pk_bf16(b[2], b[3]); return w; }
;     __device__ __forceinline__ void operator()(f32x4 (&acc)[2][2][4][2], const Unit& u, int wr, int wc, int fr, int fq) const {
;     ...
;                     const float rt = __builtin_amdgcn_rsqf(s * (1.0f / D) + RMS_EPS);
;                     const int lb = (fq << 4);
; #pragma unroll
;                     for (int j = 0; j < 4; ++j) { r0[j] = __shfl(rt, lb | j); r1[j] = __shfl(rt, lb | (4 + j)); }
;                 }
;                 f32x4 s0 = {0.f, 0.f, 0.f, 0.f}, s1 = s0, q0 = s0, q1 = s0;
; #pragma unroll
;                 for (int ai = 0; ai < 2; ++ai)
; #pragma unroll
;                     for (int m = 0; m < 4; ++m) {
;                         const int ch = ch0 + ai * HALF + m * 16;
;                         f32x4 v0 = acc[ai][bj][m][0] * r0, v1 = acc[ai][bj][m][1] * r1;
;                         if (isg) { v0 = gelu4(v0); v1 = gelu4(v1); s0 += v0; s1 += v1; q0 += v0 * v0; q1 += v1 * v1; }
;                         *(u32x4*)(base + (size_t)ch * T + tok) = pack8(v0, v1);
	global_store_dwordx4 v0, v[132:135], s[12:13]
	v_pk_mul_f32 v[64:65], v[64:65], v[202:203]
	v_pk_mul_f32 v[66:67], v[66:67], v[204:205]
	v_pk_mul_f32 v[60:61], v[60:61], v[206:207]
	v_pk_mul_f32 v[62:63], v[62:63], v[208:209]
	v_cvt_pk_bf16_f32 v226, v64, v65
	v_cvt_pk_bf16_f32 v227, v66, v67
	v_cvt_pk_bf16_f32 v228, v60, v61
	v_cvt_pk_bf16_f32 v229, v62, v63
	v_add_u32_e32 v0, 0x200000, v185
	global_store_dwordx4 v0, v[226:229], s[12:13]
	v_pk_mul_f32 v[48:49], v[48:49], v[202:203]
	v_pk_mul_f32 v[50:51], v[50:51], v[204:205]
	v_pk_mul_f32 v[44:45], v[44:45], v[206:207]
	v_pk_mul_f32 v[46:47], v[46:47], v[208:209]
	v_cvt_pk_bf16_f32 v132, v48, v49
	v_cvt_pk_bf16_f32 v133, v50, v51
	v_cvt_pk_bf16_f32 v134, v44, v45
	v_cvt_pk_bf16_f32 v135, v46, v47
	v_add_u32_e32 v0, 0x240000, v185
	global_store_dwordx4 v0, v[132:135], s[12:13]
	v_pk_mul_f32 v[32:33], v[32:33], v[202:203]
	v_pk_mul_f32 v[34:35], v[34:35], v[204:205]
	v_pk_mul_f32 v[28:29], v[28:29], v[206:207]
	v_pk_mul_f32 v[30:31], v[30:31], v[208:209]
	v_cvt_pk_bf16_f32 v226, v32, v33
	v_cvt_pk_bf16_f32 v227, v34, v35
	v_cvt_pk_bf16_f32 v228, v28, v29
	v_cvt_pk_bf16_f32 v229, v30, v31
	v_add_u32_e32 v0, 0x280000, v185
	global_store_dwordx4 v0, v[226:229], s[12:13]
	v_pk_mul_f32 v[16:17], v[16:17], v[202:203]
	v_pk_mul_f32 v[18:19], v[18:19], v[204:205]
	v_pk_mul_f32 v[12:13], v[12:13], v[206:207]
	v_pk_mul_f32 v[14:15], v[14:15], v[208:209]
	v_cvt_pk_bf16_f32 v132, v16, v17
	v_cvt_pk_bf16_f32 v133, v18, v19
	v_cvt_pk_bf16_f32 v134, v12, v13
	v_cvt_pk_bf16_f32 v135, v14, v15
	v_add_u32_e32 v0, 0x2c0000, v185
	global_store_dwordx4 v0, v[132:135], s[12:13]
	s_nop 1
	v_mov_b32_dpp v202, v251 row_newbcast:0 row_mask:0xf bank_mask:0xf
	v_mov_b32_dpp v203, v251 row_newbcast:1 row_mask:0xf bank_mask:0xf
	v_mov_b32_dpp v204, v251 row_newbcast:2 row_mask:0xf bank_mask:0xf
	v_mov_b32_dpp v205, v251 row_newbcast:3 row_mask:0xf bank_mask:0xf
	v_mov_b32_dpp v206, v251 row_newbcast:4 row_mask:0xf bank_mask:0xf
	v_mov_b32_dpp v207, v251 row_newbcast:5 row_mask:0xf bank_mask:0xf
	v_mov_b32_dpp v208, v251 row_newbcast:6 row_mask:0xf bank_mask:0xf
	v_mov_b32_dpp v209, v251 row_newbcast:7 row_mask:0xf bank_mask:0xf
	v_pk_mul_f32 v[120:121], v[120:121], v[202:203]
	v_pk_mul_f32 v[122:123], v[122:123], v[204:205]
	v_pk_mul_f32 v[116:117], v[116:117], v[206:207]
	v_pk_mul_f32 v[118:119], v[118:119], v[208:209]
	v_cvt_pk_bf16_f32 v226, v120, v121
	v_cvt_pk_bf16_f32 v227, v122, v123
	v_cvt_pk_bf16_f32 v228, v116, v117
	v_cvt_pk_bf16_f32 v229, v118, v119
	global_store_dwordx4 v185, v[226:229], s[12:13] offset:64
	v_pk_mul_f32 v[104:105], v[104:105], v[202:203]
	v_pk_mul_f32 v[106:107], v[106:107], v[204:205]
	v_pk_mul_f32 v[100:101], v[100:101], v[206:207]
	v_pk_mul_f32 v[102:103], v[102:103], v[208:209]
	v_cvt_pk_bf16_f32 v132, v104, v105
	v_cvt_pk_bf16_f32 v133, v106, v107
	v_cvt_pk_bf16_f32 v134, v100, v101
	v_cvt_pk_bf16_f32 v135, v102, v103
	v_add_u32_e32 v0, 0x40000, v185
	global_store_dwordx4 v0, v[132:135], s[12:13] offset:64
	v_pk_mul_f32 v[88:89], v[88:89], v[202:203]
	v_pk_mul_f32 v[90:91], v[90:91], v[204:205]
	v_pk_mul_f32 v[84:85], v[84:85], v[206:207]
	v_pk_mul_f32 v[86:87], v[86:87], v[208:209]
	v_cvt_pk_bf16_f32 v226, v88, v89
	v_cvt_pk_bf16_f32 v227, v90, v91
	v_cvt_pk_bf16_f32 v228, v84, v85
	v_cvt_pk_bf16_f32 v229, v86, v87
	v_add_u32_e32 v0, 0x80000, v185
	global_store_dwordx4 v0, v[226:229], s[12:13] offset:64
	v_pk_mul_f32 v[72:73], v[72:73], v[202:203]
	v_pk_mul_f32 v[74:75], v[74:75], v[204:205]
	v_pk_mul_f32 v[68:69], v[68:69], v[206:207]
	v_pk_mul_f32 v[70:71], v[70:71], v[208:209]
	v_cvt_pk_bf16_f32 v132, v72, v73
	v_cvt_pk_bf16_f32 v133, v74, v75
	v_cvt_pk_bf16_f32 v134, v68, v69
	v_cvt_pk_bf16_f32 v135, v70, v71
	v_add_u32_e32 v0, 0xc0000, v185
	global_store_dwordx4 v0, v[132:135], s[12:13] offset:64
	v_pk_mul_f32 v[56:57], v[56:57], v[202:203]
	v_pk_mul_f32 v[58:59], v[58:59], v[204:205]
	v_pk_mul_f32 v[52:53], v[52:53], v[206:207]
	v_pk_mul_f32 v[54:55], v[54:55], v[208:209]
	v_cvt_pk_bf16_f32 v226, v56, v57
	v_cvt_pk_bf16_f32 v227, v58, v59
	v_cvt_pk_bf16_f32 v228, v52, v53
	v_cvt_pk_bf16_f32 v229, v54, v55
	v_add_u32_e32 v0, 0x200000, v185
	global_store_dwordx4 v0, v[226:229], s[12:13] offset:64
	v_pk_mul_f32 v[40:41], v[40:41], v[202:203]
	v_pk_mul_f32 v[42:43], v[42:43], v[204:205]
	v_pk_mul_f32 v[36:37], v[36:37], v[206:207]
	v_pk_mul_f32 v[38:39], v[38:39], v[208:209]
	v_cvt_pk_bf16_f32 v132, v40, v41
	v_cvt_pk_bf16_f32 v133, v42, v43
	v_cvt_pk_bf16_f32 v134, v36, v37
	v_cvt_pk_bf16_f32 v135, v38, v39
	v_add_u32_e32 v0, 0x240000, v185
	global_store_dwordx4 v0, v[132:135], s[12:13] offset:64
	v_pk_mul_f32 v[24:25], v[24:25], v[202:203]
	v_pk_mul_f32 v[26:27], v[26:27], v[204:205]
	v_pk_mul_f32 v[20:21], v[20:21], v[206:207]
	v_pk_mul_f32 v[22:23], v[22:23], v[208:209]
	v_cvt_pk_bf16_f32 v226, v24, v25
	v_cvt_pk_bf16_f32 v227, v26, v27
	v_cvt_pk_bf16_f32 v228, v20, v21
	v_cvt_pk_bf16_f32 v229, v22, v23
	v_add_u32_e32 v0, 0x280000, v185
	global_store_dwordx4 v0, v[226:229], s[12:13] offset:64
	v_pk_mul_f32 v[8:9], v[8:9], v[202:203]
	v_pk_mul_f32 v[10:11], v[10:11], v[204:205]
	v_pk_mul_f32 v[4:5], v[4:5], v[206:207]
	v_pk_mul_f32 v[6:7], v[6:7], v[208:209]
	v_cvt_pk_bf16_f32 v132, v8, v9
	v_cvt_pk_bf16_f32 v133, v10, v11
	v_cvt_pk_bf16_f32 v134, v4, v5
	v_cvt_pk_bf16_f32 v135, v6, v7
	v_add_u32_e32 v0, 0x2c0000, v185
	global_store_dwordx4 v0, v[132:135], s[12:13] offset:64
	s_branch .LBB0_354

;     __device__ __forceinline__ void operator()(f32x4 (&acc)[2][2][4][2], const Unit& u, int wr, int wc, int fr, int fq) const {
;         if (u.kind == 0) {
;             const int pn = u.pn; bf16_t* base; int ldc, colt, mode;
;             if (pn < 4) { base = U; ldc = 1024; colt = pn * 256; mode = 0; }
;             else if (pn < 12) { base = Q; ldc = 1024; colt = (pn - 8) * 256; mode = 1; }
;             else if (pn < 16) { base = Kb; ldc = 1024; colt = (pn - 12) * 256; mode = 2; }
;             else { base = U; ldc = 4096; colt = (pn - 20) * 256; mode = 3; }
.LBB0_130:
.LBB0_131:
.LBB0_133:
.LBB0_135:
.LBB0_137:
.LBB0_139:
.LBB0_141:
.LBB0_143:
.LBB0_145:
.LBB0_148:
.LBB0_149:
.LBB0_150:
.LBB0_151:
.LBB0_152:
.LBB0_153:
.LBB0_154:
.LBB0_155:
.LBB0_156:
.LBB0_158:
.LBB0_159:
.LBB0_161:
.LBB0_163:
.LBB0_165:
.LBB0_167:
.LBB0_169:
.LBB0_171:
.LBB0_173:
.LBB0_176:
.LBB0_177:
.LBB0_178:
.LBB0_180:
.LBB0_181:
.LBB0_182:
.LBB0_183:
.LBB0_184:
.LBB0_185:
	s_cmp_lt_i32 s51, 4
	s_cselect_b64 s[16:17], -1, 0
	s_lshl_b32 s20, s51, 8
	s_and_b64 vcc, exec, s[16:17]
	s_cbranch_vccnz .LBB0_195
	s_cmp_gt_u32 s51, 11
	s_mov_b64 s[18:19], -1
	s_cbranch_scc0 .LBB0_192
	s_mov_b64 s[12:13], -1
	s_cmp_gt_u32 s51, 15
	s_cbranch_scc0 .LBB0_189
	s_add_i32 s21, s20, 0xffffec00
	s_mov_b64 s[18:19], 0

; #define PG8_BAR __builtin_amdgcn_s_barrier()
; template <class Epi, class SchedT, bool ALIGN_EPI, bool SP2>
; __device__ __forceinline__ void gemm_phase(LAS unsigned char* lds, const int ldk, const int nt, const SchedT& S, const Epi& E) {
;     ...
;         if constexpr (ALIGN_EPI) { if (wr == 0) PG8_BAR; }
;         E(acc, cur, wr, wc, fr, fq);
;         if (!has_next) break;
;         if (!(SchedT::kMode == 2 && cur.kind == 0)) {
; #pragma unroll
;         for (int a = 0; a < 2; ++a)
; #pragma unroll
;             for (int b = 0; b < 2; ++b)
; #pragma unroll
;                 for (int m = 0; m < 4; ++m)
; #pragma unroll
;                     for (int n = 0; n < 2; ++n) acc[a][b][m][n] = (f32x4){0.f, 0.f, 0.f, 0.f};
;         }
;         cur = nxt; cA = nA; cB = nB; ++ui;
;         if constexpr (ALIGN_EPI) { if (wr == 1) PG8_BAR; }
;     }
.LBB0_199:
.LBB0_203:
.LBB0_204:
.LBB0_206:
.LBB0_207:
.LBB0_210:
.LBB0_212:
.LBB0_213:
.LBB0_214:
.LBB0_216:
.LBB0_217:
.LBB0_218:
.LBB0_219:
.LBB0_220:
.LBB0_221:
.LBB0_222:
.LBB0_226:
.LBB0_227:
.LBB0_229:
.LBB0_230:
.LBB0_233:
.LBB0_235:
.LBB0_236:
.LBB0_237:
.LBB0_240:
.LBB0_241:
.LBB0_242:
.LBB0_243:
.LBB0_244:
.LBB0_245:
.LBB0_246:
.LBB0_247:
.LBB0_249:
.LBB0_252:
.LBB0_253:
.LBB0_254:
.LBB0_256:
.LBB0_259:
.LBB0_260:
.LBB0_261:
.LBB0_263:
.LBB0_266:
.LBB0_267:
.LBB0_268:
.LBB0_270:
.LBB0_273:
.LBB0_274:
.LBB0_275:
.LBB0_277:
.LBB0_280:
.LBB0_281:
.LBB0_282:
.LBB0_284:
.LBB0_287:
.LBB0_288:
.LBB0_289:
.LBB0_291:
.LBB0_294:
.LBB0_295:
.LBB0_296:
.LBB0_298:
.LBB0_301:
.LBB0_302:
.LBB0_303:
.LBB0_305:
.LBB0_308:
.LBB0_309:
.LBB0_310:
.LBB0_312:
.LBB0_315:
.LBB0_316:
.LBB0_317:
.LBB0_319:
.LBB0_322:
.LBB0_323:
.LBB0_324:
.LBB0_326:
.LBB0_329:
.LBB0_330:
.LBB0_331:
.LBB0_333:
.LBB0_336:
.LBB0_337:
.LBB0_338:
.LBB0_340:
.LBB0_343:
.LBB0_344:
.LBB0_345:
.LBB0_347:
.LBB0_350:
.LBB0_351:
.LBB0_352:
.LBB0_354:
	s_and_b64 vcc, exec, s[36:37]
	s_mov_b64 s[0:1], -1
	s_cbranch_vccnz .LBB0_117
	s_andn2_b64 vcc, exec, s[46:47]
	s_cbranch_vccnz .LBB0_116
	s_barrier
	s_branch .LBB0_116
